# GEMM K loops: DMA issue split across both halves, scalar prep hoisted
# speedup vs baseline: 1.1099x; 1.0062x over previous
; #define TIDX tid_opaque()
; DI void wait_vm0() { asm volatile("s_waitcnt vmcnt(0)" ::: "memory"); }
; DI h8 lds128(unsigned a) { h8 r; asm volatile("ds_read_b128 %0, %1" : "=v"(r) : "v"(a)); return r; }
; DI unsigned lds_addr(const void* p) { return (unsigned)(size_t)p; }
; DI void raw_barrier() { asm volatile("" ::: "memory"); __builtin_amdgcn_s_barrier(); asm volatile("" ::: "memory"); }
; template <bool PRE = false, class AF, class BF>
; DI void gemm256(AF aptr, BF bptr, int nk, char* smem, f4 (&acc)[8][4]) {
;   const int tid = TIDX, lane = tid & 63, wave = tid >> 6, fr = lane & 15, fq = lane >> 4, wr = wave >> 1, wc = wave & 1;
; #pragma unroll
;   for (int m = 0; m < 8; m++)
; #pragma unroll
;     for (int n = 0; n < 4; n++) acc[m][n] = (f4){0.f, 0.f, 0.f, 0.f};
;   auto issue = [&](int kt, int st) {
;     char* d = smem + st * 49152 + tid * 16;
; #pragma unroll
;     for (int i = 0; i < 8; i++) glds16(aptr(i) + kt * 64, d + i * 4096);
; #pragma unroll
;     for (int i = 0; i < 4; i++) glds16(bptr(i) + kt * 64, d + 32768 + i * 4096);
;   };
;   const unsigned sw = (unsigned)((fq ^ (fr >> 1)) << 4);
;   const unsigned offA = (wr * 128 + fr) * 128 + sw, offB = 32768 + (wc * 64 + fr) * 128 + sw;
;   const unsigned sbase = lds_addr(smem);
;   if (!PRE) { issue(0, 0); if (nk > 1) issue(1, 1); }
;   int st = 0;
; #pragma unroll 1
;   for (int kt = 0; kt < nk; kt++) {
;     if (kt + 1 < nk) asm volatile("s_waitcnt vmcnt(12)" ::: "memory"); else wait_vm0();
;     raw_barrier();
;     if (kt + 2 < nk) issue(kt + 2, st == 0 ? 2 : st - 1);
;     const unsigned base = sbase + st * 49152;
;     st = st == 2 ? 0 : st + 1;
;     h8 a0[8], b0[4], a1[8], b1[4];
; #pragma unroll
;     for (int m = 0; m < 8; m++) a0[m] = lds128(base + offA + m * 2048);
; #pragma unroll
;     for (int n = 0; n < 4; n++) b0[n] = lds128(base + offB + n * 2048);
; #pragma unroll
;     for (int m = 0; m < 8; m++) a1[m] = lds128(base + (offA ^ 64) + m * 2048);
; #pragma unroll
;     for (int n = 0; n < 4; n++) b1[n] = lds128(base + (offB ^ 64) + n * 2048);
.LBB0_225:
	v_mov_b32_e32 v0, v172
	s_mov_b32 s2, 0x8040
	v_lshlrev_b32_e32 v1, 3, v0
	v_and_b32_e32 v2, 48, v0
	v_bitop3_b32 v1, v1, v2, s36 bitop3:0x6c
	v_lshlrev_b32_e32 v2, 7, v0
	v_and_b32_e32 v3, 0xffffc780, v2
	v_and_b32_e32 v2, 0x2780, v2
	v_or_b32_e32 v4, v1, v2
	s_mov_b32 s22, s28
	v_or_b32_e32 v24, v1, v3
	v_or_b32_e32 v25, 0x8000, v4
	v_lshlrev_b32_e32 v26, 4, v0
	v_bitop3_b32 v27, v1, 64, v3 bitop3:0x36
	v_bitop3_b32 v28, v1, s2, v2 bitop3:0x36
	v_accvgpr_write_b32 a3, 0
	v_accvgpr_write_b32 a2, 0
	v_accvgpr_write_b32 a1, 0
	v_accvgpr_write_b32 a0, 0
	v_accvgpr_write_b32 a7, 0
	v_accvgpr_write_b32 a6, 0
	v_accvgpr_write_b32 a5, 0
	v_accvgpr_write_b32 a4, 0
	v_accvgpr_write_b32 a11, 0
	v_accvgpr_write_b32 a10, 0
	v_accvgpr_write_b32 a9, 0
	v_accvgpr_write_b32 a8, 0
	v_accvgpr_write_b32 a15, 0
	v_accvgpr_write_b32 a14, 0
	v_accvgpr_write_b32 a13, 0
	v_accvgpr_write_b32 a12, 0
	v_accvgpr_write_b32 a19, 0
	v_accvgpr_write_b32 a18, 0
	v_accvgpr_write_b32 a17, 0
	v_accvgpr_write_b32 a16, 0
	v_accvgpr_write_b32 a31, 0
	v_accvgpr_write_b32 a30, 0
	v_accvgpr_write_b32 a29, 0
	v_accvgpr_write_b32 a28, 0
	v_accvgpr_write_b32 a55, 0
	v_accvgpr_write_b32 a54, 0
	v_accvgpr_write_b32 a53, 0
	v_accvgpr_write_b32 a52, 0
	v_accvgpr_write_b32 a71, 0
	v_accvgpr_write_b32 a70, 0
	v_accvgpr_write_b32 a69, 0
	v_accvgpr_write_b32 a68, 0
	v_accvgpr_write_b32 a91, 0
	v_accvgpr_write_b32 a90, 0
	v_accvgpr_write_b32 a89, 0
	v_accvgpr_write_b32 a88, 0
	v_accvgpr_write_b32 a111, 0
	v_accvgpr_write_b32 a110, 0
	v_accvgpr_write_b32 a109, 0
	v_accvgpr_write_b32 a108, 0
	v_accvgpr_write_b32 a127, 0
	v_accvgpr_write_b32 a126, 0
	v_accvgpr_write_b32 a125, 0
	v_accvgpr_write_b32 a124, 0
	v_accvgpr_write_b32 a123, 0
	v_accvgpr_write_b32 a122, 0
	v_accvgpr_write_b32 a121, 0
	v_accvgpr_write_b32 a120, 0
	v_accvgpr_write_b32 a119, 0
	v_accvgpr_write_b32 a118, 0
	v_accvgpr_write_b32 a117, 0
	v_accvgpr_write_b32 a116, 0
	v_accvgpr_write_b32 a115, 0
	v_accvgpr_write_b32 a114, 0
	v_accvgpr_write_b32 a113, 0
	v_accvgpr_write_b32 a112, 0
	v_accvgpr_write_b32 a107, 0
	v_accvgpr_write_b32 a106, 0
	v_accvgpr_write_b32 a105, 0
	v_accvgpr_write_b32 a104, 0
	v_accvgpr_write_b32 a103, 0
	v_accvgpr_write_b32 a102, 0
	v_accvgpr_write_b32 a101, 0
	v_accvgpr_write_b32 a100, 0
	v_accvgpr_write_b32 a99, 0
	v_accvgpr_write_b32 a98, 0
	v_accvgpr_write_b32 a97, 0
	v_accvgpr_write_b32 a96, 0
	v_accvgpr_write_b32 a95, 0
	v_accvgpr_write_b32 a94, 0
	v_accvgpr_write_b32 a93, 0
	v_accvgpr_write_b32 a92, 0
	v_accvgpr_write_b32 a87, 0
	v_accvgpr_write_b32 a86, 0
	v_accvgpr_write_b32 a85, 0
	v_accvgpr_write_b32 a84, 0
	v_accvgpr_write_b32 a83, 0
	v_accvgpr_write_b32 a82, 0
	v_accvgpr_write_b32 a81, 0
	v_accvgpr_write_b32 a80, 0
	v_accvgpr_write_b32 a79, 0
	v_accvgpr_write_b32 a78, 0
	v_accvgpr_write_b32 a77, 0
	v_accvgpr_write_b32 a76, 0
	v_accvgpr_write_b32 a75, 0
	v_accvgpr_write_b32 a74, 0
	v_accvgpr_write_b32 a73, 0
	v_accvgpr_write_b32 a72, 0
	v_accvgpr_write_b32 a67, 0
	v_accvgpr_write_b32 a66, 0
	v_accvgpr_write_b32 a65, 0
	v_accvgpr_write_b32 a64, 0
	v_accvgpr_write_b32 a63, 0
	v_accvgpr_write_b32 a62, 0
	v_accvgpr_write_b32 a61, 0
	v_accvgpr_write_b32 a60, 0
	v_accvgpr_write_b32 a59, 0
	v_accvgpr_write_b32 a58, 0
	v_accvgpr_write_b32 a57, 0
	v_accvgpr_write_b32 a56, 0
	v_accvgpr_write_b32 a51, 0
	v_accvgpr_write_b32 a50, 0
	v_accvgpr_write_b32 a49, 0
	v_accvgpr_write_b32 a48, 0
	v_accvgpr_write_b32 a47, 0
	v_accvgpr_write_b32 a46, 0
	v_accvgpr_write_b32 a45, 0
	v_accvgpr_write_b32 a44, 0
	v_accvgpr_write_b32 a43, 0
	v_accvgpr_write_b32 a42, 0
	v_accvgpr_write_b32 a41, 0
	v_accvgpr_write_b32 a40, 0
	v_accvgpr_write_b32 a39, 0
	v_accvgpr_write_b32 a38, 0
	v_accvgpr_write_b32 a37, 0
	v_accvgpr_write_b32 a36, 0
	v_accvgpr_write_b32 a35, 0
	v_accvgpr_write_b32 a34, 0
	v_accvgpr_write_b32 a33, 0
	v_accvgpr_write_b32 a32, 0
	v_accvgpr_write_b32 a27, 0
	v_accvgpr_write_b32 a26, 0
	v_accvgpr_write_b32 a25, 0
	v_accvgpr_write_b32 a24, 0
	v_accvgpr_write_b32 a23, 0
	v_accvgpr_write_b32 a22, 0
	v_accvgpr_write_b32 a21, 0
	v_accvgpr_write_b32 a20, 0
	s_mov_b32 s6, 0
	s_mov_b64 s[2:3], 0
	s_mov_b32 s7, 0
	v_readfirstlane_b32 s100, v26
	s_waitcnt vmcnt(12)
	s_barrier
	s_add_u32 s101, s100, 0x18000
	v_lshl_add_u64 v[10:11], v[96:97], 0, s[2:3]
	s_add_u32 m0, s101, 0x0
	v_lshl_add_u64 v[14:15], v[10:11], 0, s[74:75]
	global_load_lds_dwordx4 v[14:15], off
	s_add_u32 m0, s101, 0x1000
	v_lshl_add_u64 v[14:15], v[10:11], 0, s[76:77]
	global_load_lds_dwordx4 v[14:15], off
	s_add_u32 m0, s101, 0x2000
	v_lshl_add_u64 v[14:15], v[10:11], 0, s[86:87]
	global_load_lds_dwordx4 v[14:15], off
	s_add_u32 m0, s101, 0x3000
	v_lshl_add_u64 v[14:15], v[10:11], 0, s[80:81]
	global_load_lds_dwordx4 v[14:15], off
	s_add_u32 m0, s101, 0x4000
	v_lshl_add_u64 v[14:15], v[10:11], 0, s[72:73]
	global_load_lds_dwordx4 v[14:15], off
	s_add_u32 m0, s101, 0x5000
	v_lshl_add_u64 v[14:15], v[10:11], 0, s[96:97]
	global_load_lds_dwordx4 v[14:15], off
	ds_read_b128 v[62:65], v25 offset:0
	ds_read_b128 v[66:69], v25 offset:2048
	ds_read_b128 v[70:73], v25 offset:4096
	ds_read_b128 v[74:77], v25 offset:6144
	ds_read_b128 v[30:33], v24 offset:0
	ds_read_b128 v[34:37], v24 offset:2048
	ds_read_b128 v[38:41], v24 offset:4096
	ds_read_b128 v[42:45], v24 offset:6144
	ds_read_b128 v[46:49], v24 offset:8192
	ds_read_b128 v[50:53], v24 offset:10240
	ds_read_b128 v[54:57], v24 offset:12288
	ds_read_b128 v[58:61], v24 offset:14336
; DI void wait_vm0() { asm volatile("s_waitcnt vmcnt(0)" ::: "memory"); }
; DI f4 mfma16(h8 a, h8 b, f4 c) { return __builtin_amdgcn_mfma_f32_16x16x32_f16(a, b, c, 0, 0, 0); }
; DI h8 lds128(unsigned a) { h8 r; asm volatile("ds_read_b128 %0, %1" : "=v"(r) : "v"(a)); return r; }
; DI void tie(h8& x) { asm volatile("" : "+v"(x)); }
; #define WAIT_LGKM(n) asm volatile("s_waitcnt lgkmcnt(" #n ")" ::: "memory")
; DI void raw_barrier() { asm volatile("" ::: "memory"); __builtin_amdgcn_s_barrier(); asm volatile("" ::: "memory"); }
; template <bool PRE = false, class AF, class BF>
; DI void gemm256(AF aptr, BF bptr, int nk, char* smem, f4 (&acc)[8][4]) {
;     ...
;   for (int kt = 0; kt < nk; kt++) {
;     if (kt + 1 < nk) asm volatile("s_waitcnt vmcnt(12)" ::: "memory"); else wait_vm0();
;     raw_barrier();
;     if (kt + 2 < nk) issue(kt + 2, st == 0 ? 2 : st - 1);
;     const unsigned base = sbase + st * 49152;
;     st = st == 2 ? 0 : st + 1;
;     h8 a0[8], b0[4], a1[8], b1[4];
; #pragma unroll
;     for (int m = 0; m < 8; m++) a0[m] = lds128(base + offA + m * 2048);
; #pragma unroll
;     for (int n = 0; n < 4; n++) b0[n] = lds128(base + offB + n * 2048);
; #pragma unroll
;     for (int m = 0; m < 8; m++) a1[m] = lds128(base + (offA ^ 64) + m * 2048);
; #pragma unroll
;     for (int n = 0; n < 4; n++) b1[n] = lds128(base + (offB ^ 64) + n * 2048);
;     WAIT_LGKM(12);
; #pragma unroll
;     for (int m = 0; m < 8; m++) tie(a0[m]);
; #pragma unroll
;     for (int n = 0; n < 4; n++) tie(b0[n]);
; #pragma unroll
;     for (int m = 0; m < 8; m++)
; #pragma unroll
;       for (int n = 0; n < 4; n++) acc[m][n] = mfma16(a0[m], b0[n], acc[m][n]);
.Lg_gin_loop:
	s_mul_i32 s9, s7, 0xc000
	v_add_u32_e32 v8, s9, v27
	v_add_u32_e32 v9, s9, v28
	s_add_u32 s101, s7, 2
	s_sub_u32 s8, s101, 3
	s_cmp_lt_u32 s101, 3
	s_cselect_b32 s101, s101, s8
	s_mul_i32 s101, s101, 0xc000
	s_add_u32 s101, s101, s100
	s_cmp_lt_u32 s6, 14
	s_waitcnt lgkmcnt(0)
	s_cbranch_scc0 .Lg_gin_h1n
	v_mfma_f32_16x16x32_f16 a[0:3], v[30:33], v[62:65], a[0:3]
	ds_read_b128 a[200:203], v9 offset:0
	v_mfma_f32_16x16x32_f16 a[4:7], v[30:33], v[66:69], a[4:7]
	v_lshl_add_u64 v[10:11], v[96:97], 0, s[2:3]
	s_add_u32 m0, s101, 0x6000
	v_lshl_add_u64 v[14:15], v[10:11], 0, s[12:13]
	global_load_lds_dwordx4 v[14:15], off
	v_mfma_f32_16x16x32_f16 a[8:11], v[30:33], v[70:73], a[8:11]
	ds_read_b128 a[204:207], v9 offset:2048
	v_mfma_f32_16x16x32_f16 a[12:15], v[30:33], v[74:77], a[12:15]
	v_mfma_f32_16x16x32_f16 a[16:19], v[34:37], v[62:65], a[16:19]
	ds_read_b128 a[208:211], v9 offset:4096
	v_mfma_f32_16x16x32_f16 a[28:31], v[34:37], v[66:69], a[28:31]
	s_add_u32 m0, s101, 0x7000
	v_lshl_add_u64 v[14:15], v[10:11], 0, s[16:17]
	global_load_lds_dwordx4 v[14:15], off
	v_mfma_f32_16x16x32_f16 a[52:55], v[34:37], v[70:73], a[52:55]
	ds_read_b128 a[212:215], v9 offset:6144
	v_mfma_f32_16x16x32_f16 a[68:71], v[34:37], v[74:77], a[68:71]
	v_mfma_f32_16x16x32_f16 a[88:91], v[38:41], v[62:65], a[88:91]
	ds_read_b128 v[78:81], v8 offset:0
	v_mfma_f32_16x16x32_f16 a[108:111], v[38:41], v[66:69], a[108:111]
	v_lshl_add_u64 v[12:13], v[94:95], 0, s[2:3]
	s_add_u32 m0, s101, 0x8000
	v_lshl_add_u64 v[14:15], v[12:13], 0, s[74:75]
	global_load_lds_dwordx4 v[14:15], off
	v_mfma_f32_16x16x32_f16 a[124:127], v[38:41], v[70:73], a[124:127]
	ds_read_b128 v[82:85], v8 offset:2048
	v_mfma_f32_16x16x32_f16 a[120:123], v[38:41], v[74:77], a[120:123]
	v_mfma_f32_16x16x32_f16 a[116:119], v[42:45], v[62:65], a[116:119]
	ds_read_b128 v[0:3], v8 offset:4096
	v_mfma_f32_16x16x32_f16 a[112:115], v[42:45], v[66:69], a[112:115]
	s_add_u32 m0, s101, 0x9000
	v_lshl_add_u64 v[14:15], v[12:13], 0, s[76:77]
	global_load_lds_dwordx4 v[14:15], off
	v_mfma_f32_16x16x32_f16 a[104:107], v[42:45], v[70:73], a[104:107]
	ds_read_b128 v[4:7], v8 offset:6144
	v_mfma_f32_16x16x32_f16 a[100:103], v[42:45], v[74:77], a[100:103]
	v_mfma_f32_16x16x32_f16 a[96:99], v[46:49], v[62:65], a[96:99]
	ds_read_b128 v[86:89], v8 offset:8192
	v_mfma_f32_16x16x32_f16 a[92:95], v[46:49], v[66:69], a[92:95]
	s_add_u32 m0, s101, 0xa000
	v_lshl_add_u64 v[14:15], v[12:13], 0, s[86:87]
	global_load_lds_dwordx4 v[14:15], off
	v_mfma_f32_16x16x32_f16 a[84:87], v[46:49], v[70:73], a[84:87]
	ds_read_b128 v[90:93], v8 offset:10240
	v_mfma_f32_16x16x32_f16 a[80:83], v[46:49], v[74:77], a[80:83]
	v_mfma_f32_16x16x32_f16 a[76:79], v[50:53], v[62:65], a[76:79]
	ds_read_b128 v[100:103], v8 offset:12288
	v_mfma_f32_16x16x32_f16 a[72:75], v[50:53], v[66:69], a[72:75]
	s_add_u32 m0, s101, 0xb000
	v_lshl_add_u64 v[14:15], v[12:13], 0, s[80:81]
	global_load_lds_dwordx4 v[14:15], off
	v_mfma_f32_16x16x32_f16 a[64:67], v[50:53], v[70:73], a[64:67]
	ds_read_b128 v[104:107], v8 offset:14336
	v_mfma_f32_16x16x32_f16 a[60:63], v[50:53], v[74:77], a[60:63]
	v_mfma_f32_16x16x32_f16 a[56:59], v[54:57], v[62:65], a[56:59]
	v_mfma_f32_16x16x32_f16 a[48:51], v[54:57], v[66:69], a[48:51]
	s_add_u32 s8, s7, 1
	v_mfma_f32_16x16x32_f16 a[44:47], v[54:57], v[70:73], a[44:47]
	s_cmp_eq_u32 s8, 3
	v_mfma_f32_16x16x32_f16 a[40:43], v[54:57], v[74:77], a[40:43]
	s_cselect_b32 s8, 0, s8
	v_mfma_f32_16x16x32_f16 a[36:39], v[58:61], v[62:65], a[36:39]
	s_mul_i32 s9, s8, 0xc000
	v_mfma_f32_16x16x32_f16 a[32:35], v[58:61], v[66:69], a[32:35]
	v_add_u32_e32 v22, s9, v24
	v_mfma_f32_16x16x32_f16 a[24:27], v[58:61], v[70:73], a[24:27]
	v_add_u32_e32 v23, s9, v25
	v_mfma_f32_16x16x32_f16 a[20:23], v[58:61], v[74:77], a[20:23]
	s_branch .Lg_gin_mid
.Lg_gin_h1n:
	v_mfma_f32_16x16x32_f16 a[0:3], v[30:33], v[62:65], a[0:3]
	ds_read_b128 a[200:203], v9 offset:0
	v_mfma_f32_16x16x32_f16 a[4:7], v[30:33], v[66:69], a[4:7]
	v_mfma_f32_16x16x32_f16 a[8:11], v[30:33], v[70:73], a[8:11]
	ds_read_b128 a[204:207], v9 offset:2048
	v_mfma_f32_16x16x32_f16 a[12:15], v[30:33], v[74:77], a[12:15]
	v_mfma_f32_16x16x32_f16 a[16:19], v[34:37], v[62:65], a[16:19]
	ds_read_b128 a[208:211], v9 offset:4096
	v_mfma_f32_16x16x32_f16 a[28:31], v[34:37], v[66:69], a[28:31]
	v_mfma_f32_16x16x32_f16 a[52:55], v[34:37], v[70:73], a[52:55]
	ds_read_b128 a[212:215], v9 offset:6144
	v_mfma_f32_16x16x32_f16 a[68:71], v[34:37], v[74:77], a[68:71]
	v_mfma_f32_16x16x32_f16 a[88:91], v[38:41], v[62:65], a[88:91]
	ds_read_b128 v[78:81], v8 offset:0
	v_mfma_f32_16x16x32_f16 a[108:111], v[38:41], v[66:69], a[108:111]
	v_mfma_f32_16x16x32_f16 a[124:127], v[38:41], v[70:73], a[124:127]
	ds_read_b128 v[82:85], v8 offset:2048
	v_mfma_f32_16x16x32_f16 a[120:123], v[38:41], v[74:77], a[120:123]
	v_mfma_f32_16x16x32_f16 a[116:119], v[42:45], v[62:65], a[116:119]
	ds_read_b128 v[0:3], v8 offset:4096
	v_mfma_f32_16x16x32_f16 a[112:115], v[42:45], v[66:69], a[112:115]
	v_mfma_f32_16x16x32_f16 a[104:107], v[42:45], v[70:73], a[104:107]
	ds_read_b128 v[4:7], v8 offset:6144
	v_mfma_f32_16x16x32_f16 a[100:103], v[42:45], v[74:77], a[100:103]
	v_mfma_f32_16x16x32_f16 a[96:99], v[46:49], v[62:65], a[96:99]
	ds_read_b128 v[86:89], v8 offset:8192
	v_mfma_f32_16x16x32_f16 a[92:95], v[46:49], v[66:69], a[92:95]
	v_mfma_f32_16x16x32_f16 a[84:87], v[46:49], v[70:73], a[84:87]
	ds_read_b128 v[90:93], v8 offset:10240
	v_mfma_f32_16x16x32_f16 a[80:83], v[46:49], v[74:77], a[80:83]
	v_mfma_f32_16x16x32_f16 a[76:79], v[50:53], v[62:65], a[76:79]
	ds_read_b128 v[100:103], v8 offset:12288
	v_mfma_f32_16x16x32_f16 a[72:75], v[50:53], v[66:69], a[72:75]
	v_mfma_f32_16x16x32_f16 a[64:67], v[50:53], v[70:73], a[64:67]
	ds_read_b128 v[104:107], v8 offset:14336
	v_mfma_f32_16x16x32_f16 a[60:63], v[50:53], v[74:77], a[60:63]
	v_mfma_f32_16x16x32_f16 a[56:59], v[54:57], v[62:65], a[56:59]
	v_mfma_f32_16x16x32_f16 a[48:51], v[54:57], v[66:69], a[48:51]
	s_add_u32 s8, s7, 1
	v_mfma_f32_16x16x32_f16 a[44:47], v[54:57], v[70:73], a[44:47]
	s_cmp_eq_u32 s8, 3
	v_mfma_f32_16x16x32_f16 a[40:43], v[54:57], v[74:77], a[40:43]
	s_cselect_b32 s8, 0, s8
	v_mfma_f32_16x16x32_f16 a[36:39], v[58:61], v[62:65], a[36:39]
	s_mul_i32 s9, s8, 0xc000
	v_mfma_f32_16x16x32_f16 a[32:35], v[58:61], v[66:69], a[32:35]
	v_add_u32_e32 v22, s9, v24
	v_mfma_f32_16x16x32_f16 a[24:27], v[58:61], v[70:73], a[24:27]
	v_add_u32_e32 v23, s9, v25
	v_mfma_f32_16x16x32_f16 a[20:23], v[58:61], v[74:77], a[20:23]
; DI void wait_vm0() { asm volatile("s_waitcnt vmcnt(0)" ::: "memory"); }
; DI f4 mfma16(h8 a, h8 b, f4 c) { return __builtin_amdgcn_mfma_f32_16x16x32_f16(a, b, c, 0, 0, 0); }
; DI h8 lds128(unsigned a) { h8 r; asm volatile("ds_read_b128 %0, %1" : "=v"(r) : "v"(a)); return r; }
; DI void tie(h8& x) { asm volatile("" : "+v"(x)); }
; #define WAIT_LGKM(n) asm volatile("s_waitcnt lgkmcnt(" #n ")" ::: "memory")
; DI void raw_barrier() { asm volatile("" ::: "memory"); __builtin_amdgcn_s_barrier(); asm volatile("" ::: "memory"); }
; template <bool PRE = false, class AF, class BF>
; DI void gemm256(AF aptr, BF bptr, int nk, char* smem, f4 (&acc)[8][4]) {
;     ...
;   for (int kt = 0; kt < nk; kt++) {
;     if (kt + 1 < nk) asm volatile("s_waitcnt vmcnt(12)" ::: "memory"); else wait_vm0();
;     raw_barrier();
;     if (kt + 2 < nk) issue(kt + 2, st == 0 ? 2 : st - 1);
;     const unsigned base = sbase + st * 49152;
;     st = st == 2 ? 0 : st + 1;
;     h8 a0[8], b0[4], a1[8], b1[4];
; #pragma unroll
;     for (int m = 0; m < 8; m++) a0[m] = lds128(base + offA + m * 2048);
; #pragma unroll
;     for (int n = 0; n < 4; n++) b0[n] = lds128(base + offB + n * 2048);
; #pragma unroll
;     for (int m = 0; m < 8; m++) a1[m] = lds128(base + (offA ^ 64) + m * 2048);
; #pragma unroll
;     for (int n = 0; n < 4; n++) b1[n] = lds128(base + (offB ^ 64) + n * 2048);
;     WAIT_LGKM(12);
; #pragma unroll
;     for (int m = 0; m < 8; m++) tie(a0[m]);
; #pragma unroll
;     for (int n = 0; n < 4; n++) tie(b0[n]);
; #pragma unroll
;     for (int m = 0; m < 8; m++)
; #pragma unroll
;       for (int n = 0; n < 4; n++) acc[m][n] = mfma16(a0[m], b0[n], acc[m][n]);
;     WAIT_LGKM(0);
; #pragma unroll
;     for (int m = 0; m < 8; m++) tie(a1[m]);
; #pragma unroll
;     for (int n = 0; n < 4; n++) tie(b1[n]);
; #pragma unroll
;     for (int m = 0; m < 8; m++)
; #pragma unroll
;       for (int n = 0; n < 4; n++) acc[m][n] = mfma16(a1[m], b1[n], acc[m][n]);
;   }
.Lg_gin_mid:
	s_cmp_eq_u32 s6, 15
	s_cbranch_scc1 .Lg_gin_last
	s_cmp_lt_u32 s6, 14
	s_cbranch_scc1 .Lg_gin_w12
	s_waitcnt vmcnt(0) lgkmcnt(0)
	s_branch .Lg_gin_wd
.Lg_gin_w12:
	s_waitcnt vmcnt(12) lgkmcnt(0)
.Lg_gin_wd:
	s_barrier
	s_add_u32 s2, s2, 0x80
	s_addc_u32 s3, s3, 0
	s_mul_i32 s101, s7, 0xc000
	s_add_u32 s101, s101, s100
	s_cmp_lt_u32 s6, 13
	s_cbranch_scc0 .Lg_gin_noissue
	v_mfma_f32_16x16x32_f16 a[0:3], v[78:81], a[200:203], a[0:3]
	ds_read_b128 v[62:65], v23 offset:0
	v_mfma_f32_16x16x32_f16 a[4:7], v[78:81], a[204:207], a[4:7]
	v_lshl_add_u64 v[10:11], v[96:97], 0, s[2:3]
	s_add_u32 m0, s101, 0x0
	v_lshl_add_u64 v[14:15], v[10:11], 0, s[74:75]
	global_load_lds_dwordx4 v[14:15], off
	v_mfma_f32_16x16x32_f16 a[8:11], v[78:81], a[208:211], a[8:11]
	ds_read_b128 v[66:69], v23 offset:2048
	v_mfma_f32_16x16x32_f16 a[12:15], v[78:81], a[212:215], a[12:15]
	v_mfma_f32_16x16x32_f16 a[16:19], v[82:85], a[200:203], a[16:19]
	ds_read_b128 v[70:73], v23 offset:4096
	v_mfma_f32_16x16x32_f16 a[28:31], v[82:85], a[204:207], a[28:31]
	s_add_u32 m0, s101, 0x1000
	v_lshl_add_u64 v[14:15], v[10:11], 0, s[76:77]
	global_load_lds_dwordx4 v[14:15], off
	v_mfma_f32_16x16x32_f16 a[52:55], v[82:85], a[208:211], a[52:55]
	ds_read_b128 v[74:77], v23 offset:6144
	v_mfma_f32_16x16x32_f16 a[68:71], v[82:85], a[212:215], a[68:71]
	v_mfma_f32_16x16x32_f16 a[88:91], v[0:3], a[200:203], a[88:91]
	ds_read_b128 v[30:33], v22 offset:0
	v_mfma_f32_16x16x32_f16 a[108:111], v[0:3], a[204:207], a[108:111]
	s_add_u32 m0, s101, 0x2000
	v_lshl_add_u64 v[14:15], v[10:11], 0, s[86:87]
	global_load_lds_dwordx4 v[14:15], off
	v_mfma_f32_16x16x32_f16 a[124:127], v[0:3], a[208:211], a[124:127]
	ds_read_b128 v[34:37], v22 offset:2048
	v_mfma_f32_16x16x32_f16 a[120:123], v[0:3], a[212:215], a[120:123]
	v_mfma_f32_16x16x32_f16 a[116:119], v[4:7], a[200:203], a[116:119]
	ds_read_b128 v[38:41], v22 offset:4096
	v_mfma_f32_16x16x32_f16 a[112:115], v[4:7], a[204:207], a[112:115]
	s_add_u32 m0, s101, 0x3000
	v_lshl_add_u64 v[14:15], v[10:11], 0, s[80:81]
	global_load_lds_dwordx4 v[14:15], off
	v_mfma_f32_16x16x32_f16 a[104:107], v[4:7], a[208:211], a[104:107]
	ds_read_b128 v[42:45], v22 offset:6144
	v_mfma_f32_16x16x32_f16 a[100:103], v[4:7], a[212:215], a[100:103]
	v_mfma_f32_16x16x32_f16 a[96:99], v[86:89], a[200:203], a[96:99]
	ds_read_b128 v[46:49], v22 offset:8192
	v_mfma_f32_16x16x32_f16 a[92:95], v[86:89], a[204:207], a[92:95]
	s_add_u32 m0, s101, 0x4000
	v_lshl_add_u64 v[14:15], v[10:11], 0, s[72:73]
	global_load_lds_dwordx4 v[14:15], off
	v_mfma_f32_16x16x32_f16 a[84:87], v[86:89], a[208:211], a[84:87]
	ds_read_b128 v[50:53], v22 offset:10240
	v_mfma_f32_16x16x32_f16 a[80:83], v[86:89], a[212:215], a[80:83]
	v_mfma_f32_16x16x32_f16 a[76:79], v[90:93], a[200:203], a[76:79]
	ds_read_b128 v[54:57], v22 offset:12288
	v_mfma_f32_16x16x32_f16 a[72:75], v[90:93], a[204:207], a[72:75]
	s_add_u32 m0, s101, 0x5000
	v_lshl_add_u64 v[14:15], v[10:11], 0, s[96:97]
	global_load_lds_dwordx4 v[14:15], off
	v_mfma_f32_16x16x32_f16 a[64:67], v[90:93], a[208:211], a[64:67]
	ds_read_b128 v[58:61], v22 offset:14336
	v_mfma_f32_16x16x32_f16 a[60:63], v[90:93], a[212:215], a[60:63]
	v_mfma_f32_16x16x32_f16 a[56:59], v[100:103], a[200:203], a[56:59]
	v_mfma_f32_16x16x32_f16 a[48:51], v[100:103], a[204:207], a[48:51]
	v_mfma_f32_16x16x32_f16 a[44:47], v[100:103], a[208:211], a[44:47]
	v_mfma_f32_16x16x32_f16 a[40:43], v[100:103], a[212:215], a[40:43]
	v_mfma_f32_16x16x32_f16 a[36:39], v[104:107], a[200:203], a[36:39]
	v_mfma_f32_16x16x32_f16 a[32:35], v[104:107], a[204:207], a[32:35]
	v_mfma_f32_16x16x32_f16 a[24:27], v[104:107], a[208:211], a[24:27]
	v_mfma_f32_16x16x32_f16 a[20:23], v[104:107], a[212:215], a[20:23]
	s_branch .Lg_gin_next
.Lg_gin_noissue:
	v_mfma_f32_16x16x32_f16 a[0:3], v[78:81], a[200:203], a[0:3]
	ds_read_b128 v[62:65], v23 offset:0
	v_mfma_f32_16x16x32_f16 a[4:7], v[78:81], a[204:207], a[4:7]
	v_mfma_f32_16x16x32_f16 a[8:11], v[78:81], a[208:211], a[8:11]
	ds_read_b128 v[66:69], v23 offset:2048
	v_mfma_f32_16x16x32_f16 a[12:15], v[78:81], a[212:215], a[12:15]
	v_mfma_f32_16x16x32_f16 a[16:19], v[82:85], a[200:203], a[16:19]
	ds_read_b128 v[70:73], v23 offset:4096
	v_mfma_f32_16x16x32_f16 a[28:31], v[82:85], a[204:207], a[28:31]
	v_mfma_f32_16x16x32_f16 a[52:55], v[82:85], a[208:211], a[52:55]
	ds_read_b128 v[74:77], v23 offset:6144
	v_mfma_f32_16x16x32_f16 a[68:71], v[82:85], a[212:215], a[68:71]
	v_mfma_f32_16x16x32_f16 a[88:91], v[0:3], a[200:203], a[88:91]
	ds_read_b128 v[30:33], v22 offset:0
	v_mfma_f32_16x16x32_f16 a[108:111], v[0:3], a[204:207], a[108:111]
	v_mfma_f32_16x16x32_f16 a[124:127], v[0:3], a[208:211], a[124:127]
	ds_read_b128 v[34:37], v22 offset:2048
	v_mfma_f32_16x16x32_f16 a[120:123], v[0:3], a[212:215], a[120:123]
	v_mfma_f32_16x16x32_f16 a[116:119], v[4:7], a[200:203], a[116:119]
	ds_read_b128 v[38:41], v22 offset:4096
	v_mfma_f32_16x16x32_f16 a[112:115], v[4:7], a[204:207], a[112:115]
	v_mfma_f32_16x16x32_f16 a[104:107], v[4:7], a[208:211], a[104:107]
	ds_read_b128 v[42:45], v22 offset:6144
	v_mfma_f32_16x16x32_f16 a[100:103], v[4:7], a[212:215], a[100:103]
	v_mfma_f32_16x16x32_f16 a[96:99], v[86:89], a[200:203], a[96:99]
	ds_read_b128 v[46:49], v22 offset:8192
	v_mfma_f32_16x16x32_f16 a[92:95], v[86:89], a[204:207], a[92:95]
	v_mfma_f32_16x16x32_f16 a[84:87], v[86:89], a[208:211], a[84:87]
	ds_read_b128 v[50:53], v22 offset:10240
	v_mfma_f32_16x16x32_f16 a[80:83], v[86:89], a[212:215], a[80:83]
	v_mfma_f32_16x16x32_f16 a[76:79], v[90:93], a[200:203], a[76:79]
	ds_read_b128 v[54:57], v22 offset:12288
	v_mfma_f32_16x16x32_f16 a[72:75], v[90:93], a[204:207], a[72:75]
	v_mfma_f32_16x16x32_f16 a[64:67], v[90:93], a[208:211], a[64:67]
	ds_read_b128 v[58:61], v22 offset:14336
	v_mfma_f32_16x16x32_f16 a[60:63], v[90:93], a[212:215], a[60:63]
	v_mfma_f32_16x16x32_f16 a[56:59], v[100:103], a[200:203], a[56:59]
	v_mfma_f32_16x16x32_f16 a[48:51], v[100:103], a[204:207], a[48:51]
	v_mfma_f32_16x16x32_f16 a[44:47], v[100:103], a[208:211], a[44:47]
	v_mfma_f32_16x16x32_f16 a[40:43], v[100:103], a[212:215], a[40:43]
	v_mfma_f32_16x16x32_f16 a[36:39], v[104:107], a[200:203], a[36:39]
	v_mfma_f32_16x16x32_f16 a[32:35], v[104:107], a[204:207], a[32:35]
	v_mfma_f32_16x16x32_f16 a[24:27], v[104:107], a[208:211], a[24:27]
	v_mfma_f32_16x16x32_f16 a[20:23], v[104:107], a[212:215], a[20:23]
.Lg_gin_next:
	s_mov_b32 s7, s8
	s_add_u32 s6, s6, 1
	s_branch .Lg_gin_loop

; #define TIDX tid_opaque()
; DI void wait_vm0() { asm volatile("s_waitcnt vmcnt(0)" ::: "memory"); }
; DI h8 lds128(unsigned a) { h8 r; asm volatile("ds_read_b128 %0, %1" : "=v"(r) : "v"(a)); return r; }
; DI unsigned lds_addr(const void* p) { return (unsigned)(size_t)p; }
; DI void raw_barrier() { asm volatile("" ::: "memory"); __builtin_amdgcn_s_barrier(); asm volatile("" ::: "memory"); }
; template <bool PRE = false, class AF, class BF>
; DI void gemm256(AF aptr, BF bptr, int nk, char* smem, f4 (&acc)[8][4]) {
;   const int tid = TIDX, lane = tid & 63, wave = tid >> 6, fr = lane & 15, fq = lane >> 4, wr = wave >> 1, wc = wave & 1;
; #pragma unroll
;   for (int m = 0; m < 8; m++)
; #pragma unroll
;     for (int n = 0; n < 4; n++) acc[m][n] = (f4){0.f, 0.f, 0.f, 0.f};
;   auto issue = [&](int kt, int st) {
;     char* d = smem + st * 49152 + tid * 16;
; #pragma unroll
;     for (int i = 0; i < 8; i++) glds16(aptr(i) + kt * 64, d + i * 4096);
; #pragma unroll
;     for (int i = 0; i < 4; i++) glds16(bptr(i) + kt * 64, d + 32768 + i * 4096);
;   };
;   const unsigned sw = (unsigned)((fq ^ (fr >> 1)) << 4);
;   const unsigned offA = (wr * 128 + fr) * 128 + sw, offB = 32768 + (wc * 64 + fr) * 128 + sw;
;   const unsigned sbase = lds_addr(smem);
;   if (!PRE) { issue(0, 0); if (nk > 1) issue(1, 1); }
;   int st = 0;
; #pragma unroll 1
;   for (int kt = 0; kt < nk; kt++) {
;     if (kt + 1 < nk) asm volatile("s_waitcnt vmcnt(12)" ::: "memory"); else wait_vm0();
;     raw_barrier();
;     if (kt + 2 < nk) issue(kt + 2, st == 0 ? 2 : st - 1);
;     const unsigned base = sbase + st * 49152;
;     st = st == 2 ? 0 : st + 1;
;     h8 a0[8], b0[4], a1[8], b1[4];
; #pragma unroll
;     for (int m = 0; m < 8; m++) a0[m] = lds128(base + offA + m * 2048);
; #pragma unroll
;     for (int n = 0; n < 4; n++) b0[n] = lds128(base + offB + n * 2048);
; #pragma unroll
;     for (int m = 0; m < 8; m++) a1[m] = lds128(base + (offA ^ 64) + m * 2048);
; #pragma unroll
;     for (int n = 0; n < 4; n++) b1[n] = lds128(base + (offB ^ 64) + n * 2048);
.LBB0_513:
	s_nop 0
	v_mov_b32_e32 v2, v172
	s_mov_b32 s0, 0x8040
	v_lshlrev_b32_e32 v0, 3, v2
	v_and_b32_e32 v1, 48, v2
	v_bitop3_b32 v4, v0, v1, s37 bitop3:0x6c
	v_lshlrev_b32_e32 v1, 7, v2
	v_and_b32_e32 v5, 0x2780, v1
	v_and_b32_e32 v3, 0xffffc780, v1
	v_or_b32_e32 v1, v4, v5
	v_or_b32_e32 v0, v4, v3
	v_or_b32_e32 v1, 0x8000, v1
	v_lshlrev_b32_e32 v2, 4, v2
	v_bitop3_b32 v3, v4, 64, v3 bitop3:0x36
	v_bitop3_b32 v4, v4, s0, v5 bitop3:0x36
	v_accvgpr_write_b32 a127, 0
	v_accvgpr_write_b32 a126, 0
	v_accvgpr_write_b32 a125, 0
	v_accvgpr_write_b32 a124, 0
	v_accvgpr_write_b32 a123, 0
	v_accvgpr_write_b32 a122, 0
	v_accvgpr_write_b32 a121, 0
	v_accvgpr_write_b32 a120, 0
	v_accvgpr_write_b32 a119, 0
	v_accvgpr_write_b32 a118, 0
	v_accvgpr_write_b32 a117, 0
	v_accvgpr_write_b32 a116, 0
	v_accvgpr_write_b32 a115, 0
	v_accvgpr_write_b32 a114, 0
	v_accvgpr_write_b32 a113, 0
	v_accvgpr_write_b32 a112, 0
	v_accvgpr_write_b32 a111, 0
	v_accvgpr_write_b32 a110, 0
	v_accvgpr_write_b32 a109, 0
	v_accvgpr_write_b32 a108, 0
	v_accvgpr_write_b32 a107, 0
	v_accvgpr_write_b32 a106, 0
	v_accvgpr_write_b32 a105, 0
	v_accvgpr_write_b32 a104, 0
	v_accvgpr_write_b32 a103, 0
	v_accvgpr_write_b32 a102, 0
	v_accvgpr_write_b32 a101, 0
	v_accvgpr_write_b32 a100, 0
	v_accvgpr_write_b32 a99, 0
	v_accvgpr_write_b32 a98, 0
	v_accvgpr_write_b32 a97, 0
	v_accvgpr_write_b32 a96, 0
	v_accvgpr_write_b32 a95, 0
	v_accvgpr_write_b32 a94, 0
	v_accvgpr_write_b32 a93, 0
	v_accvgpr_write_b32 a92, 0
	v_accvgpr_write_b32 a91, 0
	v_accvgpr_write_b32 a90, 0
	v_accvgpr_write_b32 a89, 0
	v_accvgpr_write_b32 a88, 0
	v_accvgpr_write_b32 a87, 0
	v_accvgpr_write_b32 a86, 0
	v_accvgpr_write_b32 a85, 0
	v_accvgpr_write_b32 a84, 0
	v_accvgpr_write_b32 a83, 0
	v_accvgpr_write_b32 a82, 0
	v_accvgpr_write_b32 a81, 0
	v_accvgpr_write_b32 a80, 0
	v_accvgpr_write_b32 a79, 0
	v_accvgpr_write_b32 a78, 0
	v_accvgpr_write_b32 a77, 0
	v_accvgpr_write_b32 a76, 0
	v_accvgpr_write_b32 a75, 0
	v_accvgpr_write_b32 a74, 0
	v_accvgpr_write_b32 a73, 0
	v_accvgpr_write_b32 a72, 0
	v_accvgpr_write_b32 a71, 0
	v_accvgpr_write_b32 a70, 0
	v_accvgpr_write_b32 a69, 0
	v_accvgpr_write_b32 a68, 0
	v_accvgpr_write_b32 a67, 0
	v_accvgpr_write_b32 a66, 0
	v_accvgpr_write_b32 a65, 0
	v_accvgpr_write_b32 a64, 0
	v_accvgpr_write_b32 a63, 0
	v_accvgpr_write_b32 a62, 0
	v_accvgpr_write_b32 a61, 0
	v_accvgpr_write_b32 a60, 0
	v_accvgpr_write_b32 a59, 0
	v_accvgpr_write_b32 a58, 0
	v_accvgpr_write_b32 a57, 0
	v_accvgpr_write_b32 a56, 0
	v_accvgpr_write_b32 a55, 0
	v_accvgpr_write_b32 a54, 0
	v_accvgpr_write_b32 a53, 0
	v_accvgpr_write_b32 a52, 0
	v_accvgpr_write_b32 a51, 0
	v_accvgpr_write_b32 a50, 0
	v_accvgpr_write_b32 a49, 0
	v_accvgpr_write_b32 a48, 0
	v_accvgpr_write_b32 a47, 0
	v_accvgpr_write_b32 a46, 0
	v_accvgpr_write_b32 a45, 0
	v_accvgpr_write_b32 a44, 0
	v_accvgpr_write_b32 a43, 0
	v_accvgpr_write_b32 a42, 0
	v_accvgpr_write_b32 a41, 0
	v_accvgpr_write_b32 a40, 0
	v_accvgpr_write_b32 a39, 0
	v_accvgpr_write_b32 a38, 0
	v_accvgpr_write_b32 a37, 0
	v_accvgpr_write_b32 a36, 0
	v_accvgpr_write_b32 a35, 0
	v_accvgpr_write_b32 a34, 0
	v_accvgpr_write_b32 a33, 0
	v_accvgpr_write_b32 a32, 0
	v_accvgpr_write_b32 a31, 0
	v_accvgpr_write_b32 a30, 0
	v_accvgpr_write_b32 a29, 0
	v_accvgpr_write_b32 a28, 0
	v_accvgpr_write_b32 a27, 0
	v_accvgpr_write_b32 a26, 0
	v_accvgpr_write_b32 a25, 0
	v_accvgpr_write_b32 a24, 0
	v_accvgpr_write_b32 a23, 0
	v_accvgpr_write_b32 a22, 0
	v_accvgpr_write_b32 a21, 0
	v_accvgpr_write_b32 a20, 0
	v_accvgpr_write_b32 a19, 0
	v_accvgpr_write_b32 a18, 0
	v_accvgpr_write_b32 a17, 0
	v_accvgpr_write_b32 a16, 0
	v_accvgpr_write_b32 a11, 0
	v_accvgpr_write_b32 a10, 0
	v_accvgpr_write_b32 a9, 0
	v_accvgpr_write_b32 a8, 0
	v_accvgpr_write_b32 a3, 0
	v_accvgpr_write_b32 a2, 0
	v_accvgpr_write_b32 a1, 0
	v_accvgpr_write_b32 a0, 0
	v_accvgpr_write_b32 a7, 0
	v_accvgpr_write_b32 a6, 0
	v_accvgpr_write_b32 a5, 0
	v_accvgpr_write_b32 a4, 0
	v_accvgpr_write_b32 a15, 0
	v_accvgpr_write_b32 a14, 0
	v_accvgpr_write_b32 a13, 0
	v_accvgpr_write_b32 a12, 0
	s_mov_b32 s10, 0
	s_mov_b64 s[0:1], 0
	s_mov_b32 s11, 0
	v_readfirstlane_b32 s100, v2
	s_waitcnt vmcnt(12)
	s_barrier
	s_add_u32 s101, s100, 0x18000
	v_lshl_add_u64 v[88:89], v[132:133], 0, s[0:1]
	s_add_u32 m0, s101, 0x0
	v_lshl_add_u64 v[92:93], v[88:89], 0, s[74:75]
	global_load_lds_dwordx4 v[92:93], off
	s_add_u32 m0, s101, 0x1000
	v_lshl_add_u64 v[92:93], v[88:89], 0, s[76:77]
	global_load_lds_dwordx4 v[92:93], off
	s_add_u32 m0, s101, 0x2000
	v_lshl_add_u64 v[92:93], v[88:89], 0, s[86:87]
	global_load_lds_dwordx4 v[92:93], off
	s_add_u32 m0, s101, 0x3000
	v_lshl_add_u64 v[92:93], v[88:89], 0, s[80:81]
	global_load_lds_dwordx4 v[92:93], off
	s_add_u32 m0, s101, 0x4000
	v_lshl_add_u64 v[92:93], v[88:89], 0, s[72:73]
	global_load_lds_dwordx4 v[92:93], off
	s_add_u32 m0, s101, 0x5000
	v_lshl_add_u64 v[92:93], v[88:89], 0, s[96:97]
	global_load_lds_dwordx4 v[92:93], off
	ds_read_b128 v[38:41], v1 offset:0
	ds_read_b128 v[42:45], v1 offset:2048
	ds_read_b128 v[46:49], v1 offset:4096
	ds_read_b128 v[50:53], v1 offset:6144
	ds_read_b128 v[6:9], v0 offset:0
	ds_read_b128 v[10:13], v0 offset:2048
	ds_read_b128 v[14:17], v0 offset:4096
	ds_read_b128 v[18:21], v0 offset:6144
	ds_read_b128 v[22:25], v0 offset:8192
	ds_read_b128 v[26:29], v0 offset:10240
	ds_read_b128 v[30:33], v0 offset:12288
	ds_read_b128 v[34:37], v0 offset:14336
; DI void wait_vm0() { asm volatile("s_waitcnt vmcnt(0)" ::: "memory"); }
; DI f4 mfma16(h8 a, h8 b, f4 c) { return __builtin_amdgcn_mfma_f32_16x16x32_f16(a, b, c, 0, 0, 0); }
; DI h8 lds128(unsigned a) { h8 r; asm volatile("ds_read_b128 %0, %1" : "=v"(r) : "v"(a)); return r; }
; DI void tie(h8& x) { asm volatile("" : "+v"(x)); }
; #define WAIT_LGKM(n) asm volatile("s_waitcnt lgkmcnt(" #n ")" ::: "memory")
; DI void raw_barrier() { asm volatile("" ::: "memory"); __builtin_amdgcn_s_barrier(); asm volatile("" ::: "memory"); }
; template <bool PRE = false, class AF, class BF>
; DI void gemm256(AF aptr, BF bptr, int nk, char* smem, f4 (&acc)[8][4]) {
;     ...
;   for (int kt = 0; kt < nk; kt++) {
;     if (kt + 1 < nk) asm volatile("s_waitcnt vmcnt(12)" ::: "memory"); else wait_vm0();
;     raw_barrier();
;     if (kt + 2 < nk) issue(kt + 2, st == 0 ? 2 : st - 1);
;     const unsigned base = sbase + st * 49152;
;     st = st == 2 ? 0 : st + 1;
;     h8 a0[8], b0[4], a1[8], b1[4];
; #pragma unroll
;     for (int m = 0; m < 8; m++) a0[m] = lds128(base + offA + m * 2048);
; #pragma unroll
;     for (int n = 0; n < 4; n++) b0[n] = lds128(base + offB + n * 2048);
; #pragma unroll
;     for (int m = 0; m < 8; m++) a1[m] = lds128(base + (offA ^ 64) + m * 2048);
; #pragma unroll
;     for (int n = 0; n < 4; n++) b1[n] = lds128(base + (offB ^ 64) + n * 2048);
;     WAIT_LGKM(12);
; #pragma unroll
;     for (int m = 0; m < 8; m++) tie(a0[m]);
; #pragma unroll
;     for (int n = 0; n < 4; n++) tie(b0[n]);
; #pragma unroll
;     for (int m = 0; m < 8; m++)
; #pragma unroll
;       for (int n = 0; n < 4; n++) acc[m][n] = mfma16(a0[m], b0[n], acc[m][n]);
.Lg_gout_loop:
	s_mul_i32 s21, s11, 0xc000
	v_add_u32_e32 v86, s21, v3
	v_add_u32_e32 v87, s21, v4
	s_add_u32 s101, s11, 2
	s_sub_u32 s20, s101, 3
	s_cmp_lt_u32 s101, 3
	s_cselect_b32 s101, s101, s20
	s_mul_i32 s101, s101, 0xc000
	s_add_u32 s101, s101, s100
	s_cmp_lt_u32 s10, 14
	s_waitcnt lgkmcnt(0)
	s_cbranch_scc0 .Lg_gout_h1n
	v_mfma_f32_16x16x32_f16 a[124:127], v[6:9], v[38:41], a[124:127]
	ds_read_b128 a[200:203], v87 offset:0
	v_mfma_f32_16x16x32_f16 a[120:123], v[6:9], v[42:45], a[120:123]
	v_lshl_add_u64 v[88:89], v[132:133], 0, s[0:1]
	s_add_u32 m0, s101, 0x6000
	v_lshl_add_u64 v[92:93], v[88:89], 0, s[12:13]
	global_load_lds_dwordx4 v[92:93], off
	v_mfma_f32_16x16x32_f16 a[116:119], v[6:9], v[46:49], a[116:119]
	ds_read_b128 a[204:207], v87 offset:2048
	v_mfma_f32_16x16x32_f16 a[112:115], v[6:9], v[50:53], a[112:115]
	v_mfma_f32_16x16x32_f16 a[108:111], v[10:13], v[38:41], a[108:111]
	ds_read_b128 a[208:211], v87 offset:4096
	v_mfma_f32_16x16x32_f16 a[104:107], v[10:13], v[42:45], a[104:107]
	s_add_u32 m0, s101, 0x7000
	v_lshl_add_u64 v[92:93], v[88:89], 0, s[16:17]
	global_load_lds_dwordx4 v[92:93], off
	v_mfma_f32_16x16x32_f16 a[100:103], v[10:13], v[46:49], a[100:103]
	ds_read_b128 a[212:215], v87 offset:6144
	v_mfma_f32_16x16x32_f16 a[96:99], v[10:13], v[50:53], a[96:99]
	v_mfma_f32_16x16x32_f16 a[92:95], v[14:17], v[38:41], a[92:95]
	ds_read_b128 v[54:57], v86 offset:0
	v_mfma_f32_16x16x32_f16 a[88:91], v[14:17], v[42:45], a[88:91]
	v_lshl_add_u64 v[90:91], v[134:135], 0, s[0:1]
	s_add_u32 m0, s101, 0x8000
	v_lshl_add_u64 v[92:93], v[90:91], 0, s[74:75]
	global_load_lds_dwordx4 v[92:93], off
	v_mfma_f32_16x16x32_f16 a[84:87], v[14:17], v[46:49], a[84:87]
	ds_read_b128 v[58:61], v86 offset:2048
	v_mfma_f32_16x16x32_f16 a[80:83], v[14:17], v[50:53], a[80:83]
	v_mfma_f32_16x16x32_f16 a[76:79], v[18:21], v[38:41], a[76:79]
	ds_read_b128 v[62:65], v86 offset:4096
	v_mfma_f32_16x16x32_f16 a[72:75], v[18:21], v[42:45], a[72:75]
	s_add_u32 m0, s101, 0x9000
	v_lshl_add_u64 v[92:93], v[90:91], 0, s[76:77]
	global_load_lds_dwordx4 v[92:93], off
	v_mfma_f32_16x16x32_f16 a[68:71], v[18:21], v[46:49], a[68:71]
	ds_read_b128 v[66:69], v86 offset:6144
	v_mfma_f32_16x16x32_f16 a[64:67], v[18:21], v[50:53], a[64:67]
	v_mfma_f32_16x16x32_f16 a[60:63], v[22:25], v[38:41], a[60:63]
	ds_read_b128 v[70:73], v86 offset:8192
	v_mfma_f32_16x16x32_f16 a[56:59], v[22:25], v[42:45], a[56:59]
	s_add_u32 m0, s101, 0xa000
	v_lshl_add_u64 v[92:93], v[90:91], 0, s[86:87]
	global_load_lds_dwordx4 v[92:93], off
	v_mfma_f32_16x16x32_f16 a[52:55], v[22:25], v[46:49], a[52:55]
	ds_read_b128 v[74:77], v86 offset:10240
	v_mfma_f32_16x16x32_f16 a[48:51], v[22:25], v[50:53], a[48:51]
	v_mfma_f32_16x16x32_f16 a[44:47], v[26:29], v[38:41], a[44:47]
	ds_read_b128 v[78:81], v86 offset:12288
	v_mfma_f32_16x16x32_f16 a[40:43], v[26:29], v[42:45], a[40:43]
	s_add_u32 m0, s101, 0xb000
	v_lshl_add_u64 v[92:93], v[90:91], 0, s[80:81]
	global_load_lds_dwordx4 v[92:93], off
	v_mfma_f32_16x16x32_f16 a[36:39], v[26:29], v[46:49], a[36:39]
	ds_read_b128 v[82:85], v86 offset:14336
	v_mfma_f32_16x16x32_f16 a[32:35], v[26:29], v[50:53], a[32:35]
	v_mfma_f32_16x16x32_f16 a[28:31], v[30:33], v[38:41], a[28:31]
	v_mfma_f32_16x16x32_f16 a[24:27], v[30:33], v[42:45], a[24:27]
	s_add_u32 s20, s11, 1
	v_mfma_f32_16x16x32_f16 a[20:23], v[30:33], v[46:49], a[20:23]
	s_cmp_eq_u32 s20, 3
	v_mfma_f32_16x16x32_f16 a[16:19], v[30:33], v[50:53], a[16:19]
	s_cselect_b32 s20, 0, s20
	v_mfma_f32_16x16x32_f16 a[8:11], v[34:37], v[38:41], a[8:11]
	s_mul_i32 s21, s20, 0xc000
	v_mfma_f32_16x16x32_f16 a[0:3], v[34:37], v[42:45], a[0:3]
	v_add_u32_e32 v100, s21, v0
	v_mfma_f32_16x16x32_f16 a[4:7], v[34:37], v[46:49], a[4:7]
	v_add_u32_e32 v101, s21, v1
	v_mfma_f32_16x16x32_f16 a[12:15], v[34:37], v[50:53], a[12:15]
	s_branch .Lg_gout_mid
.Lg_gout_h1n:
	v_mfma_f32_16x16x32_f16 a[124:127], v[6:9], v[38:41], a[124:127]
	ds_read_b128 a[200:203], v87 offset:0
	v_mfma_f32_16x16x32_f16 a[120:123], v[6:9], v[42:45], a[120:123]
	v_mfma_f32_16x16x32_f16 a[116:119], v[6:9], v[46:49], a[116:119]
	ds_read_b128 a[204:207], v87 offset:2048
	v_mfma_f32_16x16x32_f16 a[112:115], v[6:9], v[50:53], a[112:115]
	v_mfma_f32_16x16x32_f16 a[108:111], v[10:13], v[38:41], a[108:111]
	ds_read_b128 a[208:211], v87 offset:4096
	v_mfma_f32_16x16x32_f16 a[104:107], v[10:13], v[42:45], a[104:107]
	v_mfma_f32_16x16x32_f16 a[100:103], v[10:13], v[46:49], a[100:103]
	ds_read_b128 a[212:215], v87 offset:6144
	v_mfma_f32_16x16x32_f16 a[96:99], v[10:13], v[50:53], a[96:99]
	v_mfma_f32_16x16x32_f16 a[92:95], v[14:17], v[38:41], a[92:95]
	ds_read_b128 v[54:57], v86 offset:0
	v_mfma_f32_16x16x32_f16 a[88:91], v[14:17], v[42:45], a[88:91]
	v_mfma_f32_16x16x32_f16 a[84:87], v[14:17], v[46:49], a[84:87]
	ds_read_b128 v[58:61], v86 offset:2048
	v_mfma_f32_16x16x32_f16 a[80:83], v[14:17], v[50:53], a[80:83]
	v_mfma_f32_16x16x32_f16 a[76:79], v[18:21], v[38:41], a[76:79]
	ds_read_b128 v[62:65], v86 offset:4096
	v_mfma_f32_16x16x32_f16 a[72:75], v[18:21], v[42:45], a[72:75]
	v_mfma_f32_16x16x32_f16 a[68:71], v[18:21], v[46:49], a[68:71]
	ds_read_b128 v[66:69], v86 offset:6144
	v_mfma_f32_16x16x32_f16 a[64:67], v[18:21], v[50:53], a[64:67]
	v_mfma_f32_16x16x32_f16 a[60:63], v[22:25], v[38:41], a[60:63]
	ds_read_b128 v[70:73], v86 offset:8192
	v_mfma_f32_16x16x32_f16 a[56:59], v[22:25], v[42:45], a[56:59]
	v_mfma_f32_16x16x32_f16 a[52:55], v[22:25], v[46:49], a[52:55]
	ds_read_b128 v[74:77], v86 offset:10240
	v_mfma_f32_16x16x32_f16 a[48:51], v[22:25], v[50:53], a[48:51]
	v_mfma_f32_16x16x32_f16 a[44:47], v[26:29], v[38:41], a[44:47]
	ds_read_b128 v[78:81], v86 offset:12288
	v_mfma_f32_16x16x32_f16 a[40:43], v[26:29], v[42:45], a[40:43]
	v_mfma_f32_16x16x32_f16 a[36:39], v[26:29], v[46:49], a[36:39]
	ds_read_b128 v[82:85], v86 offset:14336
	v_mfma_f32_16x16x32_f16 a[32:35], v[26:29], v[50:53], a[32:35]
	v_mfma_f32_16x16x32_f16 a[28:31], v[30:33], v[38:41], a[28:31]
	v_mfma_f32_16x16x32_f16 a[24:27], v[30:33], v[42:45], a[24:27]
	s_add_u32 s20, s11, 1
	v_mfma_f32_16x16x32_f16 a[20:23], v[30:33], v[46:49], a[20:23]
	s_cmp_eq_u32 s20, 3
	v_mfma_f32_16x16x32_f16 a[16:19], v[30:33], v[50:53], a[16:19]
	s_cselect_b32 s20, 0, s20
	v_mfma_f32_16x16x32_f16 a[8:11], v[34:37], v[38:41], a[8:11]
	s_mul_i32 s21, s20, 0xc000
	v_mfma_f32_16x16x32_f16 a[0:3], v[34:37], v[42:45], a[0:3]
	v_add_u32_e32 v100, s21, v0
	v_mfma_f32_16x16x32_f16 a[4:7], v[34:37], v[46:49], a[4:7]
	v_add_u32_e32 v101, s21, v1
	v_mfma_f32_16x16x32_f16 a[12:15], v[34:37], v[50:53], a[12:15]
.Lg_gout_mid:
	s_cmp_eq_u32 s10, 15
	s_cbranch_scc1 .Lg_gout_last
	s_cmp_lt_u32 s10, 14
	s_cbranch_scc1 .Lg_gout_w12
	s_waitcnt vmcnt(0) lgkmcnt(0)
	s_branch .Lg_gout_wd

; DI void wait_vm0() { asm volatile("s_waitcnt vmcnt(0)" ::: "memory"); }
; DI f4 mfma16(h8 a, h8 b, f4 c) { return __builtin_amdgcn_mfma_f32_16x16x32_f16(a, b, c, 0, 0, 0); }
; DI h8 lds128(unsigned a) { h8 r; asm volatile("ds_read_b128 %0, %1" : "=v"(r) : "v"(a)); return r; }
; DI void tie(h8& x) { asm volatile("" : "+v"(x)); }
; #define WAIT_LGKM(n) asm volatile("s_waitcnt lgkmcnt(" #n ")" ::: "memory")
; DI void raw_barrier() { asm volatile("" ::: "memory"); __builtin_amdgcn_s_barrier(); asm volatile("" ::: "memory"); }
; template <bool PRE = false, class AF, class BF>
; DI void gemm256(AF aptr, BF bptr, int nk, char* smem, f4 (&acc)[8][4]) {
;     ...
;   for (int kt = 0; kt < nk; kt++) {
;     if (kt + 1 < nk) asm volatile("s_waitcnt vmcnt(12)" ::: "memory"); else wait_vm0();
;     raw_barrier();
;     if (kt + 2 < nk) issue(kt + 2, st == 0 ? 2 : st - 1);
;     const unsigned base = sbase + st * 49152;
;     st = st == 2 ? 0 : st + 1;
;     h8 a0[8], b0[4], a1[8], b1[4];
; #pragma unroll
;     for (int m = 0; m < 8; m++) a0[m] = lds128(base + offA + m * 2048);
; #pragma unroll
;     for (int n = 0; n < 4; n++) b0[n] = lds128(base + offB + n * 2048);
; #pragma unroll
;     for (int m = 0; m < 8; m++) a1[m] = lds128(base + (offA ^ 64) + m * 2048);
; #pragma unroll
;     for (int n = 0; n < 4; n++) b1[n] = lds128(base + (offB ^ 64) + n * 2048);
;     WAIT_LGKM(12);
; #pragma unroll
;     for (int m = 0; m < 8; m++) tie(a0[m]);
; #pragma unroll
;     for (int n = 0; n < 4; n++) tie(b0[n]);
; #pragma unroll
;     for (int m = 0; m < 8; m++)
; #pragma unroll
;       for (int n = 0; n < 4; n++) acc[m][n] = mfma16(a0[m], b0[n], acc[m][n]);
;     WAIT_LGKM(0);
; #pragma unroll
;     for (int m = 0; m < 8; m++) tie(a1[m]);
; #pragma unroll
;     for (int n = 0; n < 4; n++) tie(b1[n]);
; #pragma unroll
;     for (int m = 0; m < 8; m++)
; #pragma unroll
;       for (int n = 0; n < 4; n++) acc[m][n] = mfma16(a1[m], b1[n], acc[m][n]);
;   }
.Lg_gout_wd:
	s_barrier
	s_add_u32 s0, s0, 0x80
	s_addc_u32 s1, s1, 0
	s_mul_i32 s101, s11, 0xc000
	s_add_u32 s101, s101, s100
	s_cmp_lt_u32 s10, 13
	s_cbranch_scc0 .Lg_gout_noissue
	v_mfma_f32_16x16x32_f16 a[124:127], v[54:57], a[200:203], a[124:127]
	ds_read_b128 v[38:41], v101 offset:0
	v_mfma_f32_16x16x32_f16 a[120:123], v[54:57], a[204:207], a[120:123]
	v_lshl_add_u64 v[88:89], v[132:133], 0, s[0:1]
	s_add_u32 m0, s101, 0x0
	v_lshl_add_u64 v[92:93], v[88:89], 0, s[74:75]
	global_load_lds_dwordx4 v[92:93], off
	v_mfma_f32_16x16x32_f16 a[116:119], v[54:57], a[208:211], a[116:119]
	ds_read_b128 v[42:45], v101 offset:2048
	v_mfma_f32_16x16x32_f16 a[112:115], v[54:57], a[212:215], a[112:115]
	v_mfma_f32_16x16x32_f16 a[108:111], v[58:61], a[200:203], a[108:111]
	ds_read_b128 v[46:49], v101 offset:4096
	v_mfma_f32_16x16x32_f16 a[104:107], v[58:61], a[204:207], a[104:107]
	s_add_u32 m0, s101, 0x1000
	v_lshl_add_u64 v[92:93], v[88:89], 0, s[76:77]
	global_load_lds_dwordx4 v[92:93], off
	v_mfma_f32_16x16x32_f16 a[100:103], v[58:61], a[208:211], a[100:103]
	ds_read_b128 v[50:53], v101 offset:6144
	v_mfma_f32_16x16x32_f16 a[96:99], v[58:61], a[212:215], a[96:99]
	v_mfma_f32_16x16x32_f16 a[92:95], v[62:65], a[200:203], a[92:95]
	ds_read_b128 v[6:9], v100 offset:0
	v_mfma_f32_16x16x32_f16 a[88:91], v[62:65], a[204:207], a[88:91]
	s_add_u32 m0, s101, 0x2000
	v_lshl_add_u64 v[92:93], v[88:89], 0, s[86:87]
	global_load_lds_dwordx4 v[92:93], off
	v_mfma_f32_16x16x32_f16 a[84:87], v[62:65], a[208:211], a[84:87]
	ds_read_b128 v[10:13], v100 offset:2048
	v_mfma_f32_16x16x32_f16 a[80:83], v[62:65], a[212:215], a[80:83]
	v_mfma_f32_16x16x32_f16 a[76:79], v[66:69], a[200:203], a[76:79]
	ds_read_b128 v[14:17], v100 offset:4096
	v_mfma_f32_16x16x32_f16 a[72:75], v[66:69], a[204:207], a[72:75]
	s_add_u32 m0, s101, 0x3000
	v_lshl_add_u64 v[92:93], v[88:89], 0, s[80:81]
	global_load_lds_dwordx4 v[92:93], off
	v_mfma_f32_16x16x32_f16 a[68:71], v[66:69], a[208:211], a[68:71]
	ds_read_b128 v[18:21], v100 offset:6144
	v_mfma_f32_16x16x32_f16 a[64:67], v[66:69], a[212:215], a[64:67]
	v_mfma_f32_16x16x32_f16 a[60:63], v[70:73], a[200:203], a[60:63]
	ds_read_b128 v[22:25], v100 offset:8192
	v_mfma_f32_16x16x32_f16 a[56:59], v[70:73], a[204:207], a[56:59]
	s_add_u32 m0, s101, 0x4000
	v_lshl_add_u64 v[92:93], v[88:89], 0, s[72:73]
	global_load_lds_dwordx4 v[92:93], off
	v_mfma_f32_16x16x32_f16 a[52:55], v[70:73], a[208:211], a[52:55]
	ds_read_b128 v[26:29], v100 offset:10240
	v_mfma_f32_16x16x32_f16 a[48:51], v[70:73], a[212:215], a[48:51]
	v_mfma_f32_16x16x32_f16 a[44:47], v[74:77], a[200:203], a[44:47]
	ds_read_b128 v[30:33], v100 offset:12288
	v_mfma_f32_16x16x32_f16 a[40:43], v[74:77], a[204:207], a[40:43]
	s_add_u32 m0, s101, 0x5000
	v_lshl_add_u64 v[92:93], v[88:89], 0, s[96:97]
	global_load_lds_dwordx4 v[92:93], off
	v_mfma_f32_16x16x32_f16 a[36:39], v[74:77], a[208:211], a[36:39]
	ds_read_b128 v[34:37], v100 offset:14336
	v_mfma_f32_16x16x32_f16 a[32:35], v[74:77], a[212:215], a[32:35]
	v_mfma_f32_16x16x32_f16 a[28:31], v[78:81], a[200:203], a[28:31]
	v_mfma_f32_16x16x32_f16 a[24:27], v[78:81], a[204:207], a[24:27]
	v_mfma_f32_16x16x32_f16 a[20:23], v[78:81], a[208:211], a[20:23]
	v_mfma_f32_16x16x32_f16 a[16:19], v[78:81], a[212:215], a[16:19]
	v_mfma_f32_16x16x32_f16 a[8:11], v[82:85], a[200:203], a[8:11]
	v_mfma_f32_16x16x32_f16 a[0:3], v[82:85], a[204:207], a[0:3]
	v_mfma_f32_16x16x32_f16 a[4:7], v[82:85], a[208:211], a[4:7]
	v_mfma_f32_16x16x32_f16 a[12:15], v[82:85], a[212:215], a[12:15]
	s_branch .Lg_gout_next
.Lg_gout_noissue:
	v_mfma_f32_16x16x32_f16 a[124:127], v[54:57], a[200:203], a[124:127]
	ds_read_b128 v[38:41], v101 offset:0
	v_mfma_f32_16x16x32_f16 a[120:123], v[54:57], a[204:207], a[120:123]
	v_mfma_f32_16x16x32_f16 a[116:119], v[54:57], a[208:211], a[116:119]
	ds_read_b128 v[42:45], v101 offset:2048
	v_mfma_f32_16x16x32_f16 a[112:115], v[54:57], a[212:215], a[112:115]
	v_mfma_f32_16x16x32_f16 a[108:111], v[58:61], a[200:203], a[108:111]
	ds_read_b128 v[46:49], v101 offset:4096
	v_mfma_f32_16x16x32_f16 a[104:107], v[58:61], a[204:207], a[104:107]
	v_mfma_f32_16x16x32_f16 a[100:103], v[58:61], a[208:211], a[100:103]
	ds_read_b128 v[50:53], v101 offset:6144
	v_mfma_f32_16x16x32_f16 a[96:99], v[58:61], a[212:215], a[96:99]
	v_mfma_f32_16x16x32_f16 a[92:95], v[62:65], a[200:203], a[92:95]
	ds_read_b128 v[6:9], v100 offset:0
	v_mfma_f32_16x16x32_f16 a[88:91], v[62:65], a[204:207], a[88:91]
	v_mfma_f32_16x16x32_f16 a[84:87], v[62:65], a[208:211], a[84:87]
	ds_read_b128 v[10:13], v100 offset:2048
	v_mfma_f32_16x16x32_f16 a[80:83], v[62:65], a[212:215], a[80:83]
	v_mfma_f32_16x16x32_f16 a[76:79], v[66:69], a[200:203], a[76:79]
	ds_read_b128 v[14:17], v100 offset:4096
	v_mfma_f32_16x16x32_f16 a[72:75], v[66:69], a[204:207], a[72:75]
	v_mfma_f32_16x16x32_f16 a[68:71], v[66:69], a[208:211], a[68:71]
	ds_read_b128 v[18:21], v100 offset:6144
	v_mfma_f32_16x16x32_f16 a[64:67], v[66:69], a[212:215], a[64:67]
	v_mfma_f32_16x16x32_f16 a[60:63], v[70:73], a[200:203], a[60:63]
	ds_read_b128 v[22:25], v100 offset:8192
	v_mfma_f32_16x16x32_f16 a[56:59], v[70:73], a[204:207], a[56:59]
	v_mfma_f32_16x16x32_f16 a[52:55], v[70:73], a[208:211], a[52:55]
	ds_read_b128 v[26:29], v100 offset:10240
	v_mfma_f32_16x16x32_f16 a[48:51], v[70:73], a[212:215], a[48:51]
	v_mfma_f32_16x16x32_f16 a[44:47], v[74:77], a[200:203], a[44:47]
	ds_read_b128 v[30:33], v100 offset:12288
	v_mfma_f32_16x16x32_f16 a[40:43], v[74:77], a[204:207], a[40:43]
	v_mfma_f32_16x16x32_f16 a[36:39], v[74:77], a[208:211], a[36:39]
	ds_read_b128 v[34:37], v100 offset:14336
	v_mfma_f32_16x16x32_f16 a[32:35], v[74:77], a[212:215], a[32:35]
	v_mfma_f32_16x16x32_f16 a[28:31], v[78:81], a[200:203], a[28:31]
	v_mfma_f32_16x16x32_f16 a[24:27], v[78:81], a[204:207], a[24:27]
	v_mfma_f32_16x16x32_f16 a[20:23], v[78:81], a[208:211], a[20:23]
	v_mfma_f32_16x16x32_f16 a[16:19], v[78:81], a[212:215], a[16:19]
	v_mfma_f32_16x16x32_f16 a[8:11], v[82:85], a[200:203], a[8:11]
	v_mfma_f32_16x16x32_f16 a[0:3], v[82:85], a[204:207], a[0:3]
	v_mfma_f32_16x16x32_f16 a[4:7], v[82:85], a[208:211], a[4:7]
	v_mfma_f32_16x16x32_f16 a[12:15], v[82:85], a[212:215], a[12:15]
.Lg_gout_next:
	s_mov_b32 s11, s20
	s_add_u32 s10, s10, 1
	s_branch .Lg_gout_loop

; #define TIDX tid_opaque()
; DI void wait_vm0() { asm volatile("s_waitcnt vmcnt(0)" ::: "memory"); }
; DI h8 lds128(unsigned a) { h8 r; asm volatile("ds_read_b128 %0, %1" : "=v"(r) : "v"(a)); return r; }
; DI unsigned lds_addr(const void* p) { return (unsigned)(size_t)p; }
; DI void raw_barrier() { asm volatile("" ::: "memory"); __builtin_amdgcn_s_barrier(); asm volatile("" ::: "memory"); }
; template <bool PRE = false, class AF, class BF>
; DI void gemm256(AF aptr, BF bptr, int nk, char* smem, f4 (&acc)[8][4]) {
;   const int tid = TIDX, lane = tid & 63, wave = tid >> 6, fr = lane & 15, fq = lane >> 4, wr = wave >> 1, wc = wave & 1;
; #pragma unroll
;   for (int m = 0; m < 8; m++)
; #pragma unroll
;     for (int n = 0; n < 4; n++) acc[m][n] = (f4){0.f, 0.f, 0.f, 0.f};
;   auto issue = [&](int kt, int st) {
;     char* d = smem + st * 49152 + tid * 16;
; #pragma unroll
;     for (int i = 0; i < 8; i++) glds16(aptr(i) + kt * 64, d + i * 4096);
; #pragma unroll
;     for (int i = 0; i < 4; i++) glds16(bptr(i) + kt * 64, d + 32768 + i * 4096);
;   };
;   const unsigned sw = (unsigned)((fq ^ (fr >> 1)) << 4);
;   const unsigned offA = (wr * 128 + fr) * 128 + sw, offB = 32768 + (wc * 64 + fr) * 128 + sw;
;   const unsigned sbase = lds_addr(smem);
;   if (!PRE) { issue(0, 0); if (nk > 1) issue(1, 1); }
;   int st = 0;
; #pragma unroll 1
;   for (int kt = 0; kt < nk; kt++) {
;     if (kt + 1 < nk) asm volatile("s_waitcnt vmcnt(12)" ::: "memory"); else wait_vm0();
;     raw_barrier();
;     if (kt + 2 < nk) issue(kt + 2, st == 0 ? 2 : st - 1);
;     const unsigned base = sbase + st * 49152;
;     st = st == 2 ? 0 : st + 1;
;     h8 a0[8], b0[4], a1[8], b1[4];
; #pragma unroll
;     for (int m = 0; m < 8; m++) a0[m] = lds128(base + offA + m * 2048);
; #pragma unroll
;     for (int n = 0; n < 4; n++) b0[n] = lds128(base + offB + n * 2048);
.LBB0_578:
	v_mov_b32_e32 v5, v172
	s_mov_b32 s5, 0x8040
	v_lshlrev_b32_e32 v7, 3, v5
	v_and_b32_e32 v9, 48, v5
	v_bitop3_b32 v7, v7, v9, s37 bitop3:0x6c
	v_lshlrev_b32_e32 v9, 7, v5
	v_and_b32_e32 v11, 0xffffc780, v9
	v_and_b32_e32 v9, 0x2780, v9
	v_or_b32_e32 v13, v7, v9
	v_or_b32_e32 v33, v7, v11
	v_or_b32_e32 v35, 0x8000, v13
	v_lshlrev_b32_e32 v37, 4, v5
	v_bitop3_b32 v39, v7, 64, v11 bitop3:0x36
	v_bitop3_b32 v41, v7, s5, v9 bitop3:0x36
	v_ashrrev_i32_e32 v19, 31, v18
	v_ashrrev_i32_e32 v17, 31, v16
	v_ashrrev_i32_e32 v15, 31, v14
	v_ashrrev_i32_e32 v13, 31, v12
	v_ashrrev_i32_e32 v11, 31, v10
	v_ashrrev_i32_e32 v9, 31, v8
	v_ashrrev_i32_e32 v7, 31, v6
	v_ashrrev_i32_e32 v5, 31, v4
	v_lshlrev_b64 v[18:19], 11, v[18:19]
	v_lshlrev_b64 v[16:17], 11, v[16:17]
	v_lshlrev_b64 v[14:15], 11, v[14:15]
	v_lshlrev_b64 v[12:13], 11, v[12:13]
	v_lshlrev_b64 v[10:11], 11, v[10:11]
	v_lshlrev_b64 v[8:9], 11, v[8:9]
	v_lshlrev_b64 v[6:7], 11, v[6:7]
	v_lshlrev_b64 v[4:5], 11, v[4:5]
	v_lshl_add_u64 v[58:59], v[2:3], 0, v[48:49]
	v_lshl_add_u64 v[60:61], v[0:1], 0, v[48:49]
	v_lshl_add_u64 v[62:63], v[54:55], 0, v[4:5]
	v_lshl_add_u64 v[64:65], v[54:55], 0, v[6:7]
	v_lshl_add_u64 v[66:67], v[54:55], 0, v[8:9]
	v_lshl_add_u64 v[68:69], v[54:55], 0, v[10:11]
	v_lshl_add_u64 v[70:71], v[54:55], 0, v[12:13]
	v_lshl_add_u64 v[72:73], v[54:55], 0, v[14:15]
	v_lshl_add_u64 v[74:75], v[54:55], 0, v[16:17]
	v_lshl_add_u64 v[76:77], v[54:55], 0, v[18:19]
	v_accvgpr_write_b32 a3, 0
	v_accvgpr_write_b32 a2, 0
	v_accvgpr_write_b32 a1, 0
	v_accvgpr_write_b32 a0, 0
	v_accvgpr_write_b32 a7, 0
	v_accvgpr_write_b32 a6, 0
	v_accvgpr_write_b32 a5, 0
	v_accvgpr_write_b32 a4, 0
	v_accvgpr_write_b32 a11, 0
	v_accvgpr_write_b32 a10, 0
	v_accvgpr_write_b32 a9, 0
	v_accvgpr_write_b32 a8, 0
	v_accvgpr_write_b32 a19, 0
	v_accvgpr_write_b32 a18, 0
	v_accvgpr_write_b32 a17, 0
	v_accvgpr_write_b32 a16, 0
	v_accvgpr_write_b32 a35, 0
	v_accvgpr_write_b32 a34, 0
	v_accvgpr_write_b32 a33, 0
	v_accvgpr_write_b32 a32, 0
	v_accvgpr_write_b32 a51, 0
	v_accvgpr_write_b32 a50, 0
	v_accvgpr_write_b32 a49, 0
	v_accvgpr_write_b32 a48, 0
	v_accvgpr_write_b32 a67, 0
	v_accvgpr_write_b32 a66, 0
	v_accvgpr_write_b32 a65, 0
	v_accvgpr_write_b32 a64, 0
	v_accvgpr_write_b32 a83, 0
	v_accvgpr_write_b32 a82, 0
	v_accvgpr_write_b32 a81, 0
	v_accvgpr_write_b32 a80, 0
	v_accvgpr_write_b32 a99, 0
	v_accvgpr_write_b32 a98, 0
	v_accvgpr_write_b32 a97, 0
	v_accvgpr_write_b32 a96, 0
	v_accvgpr_write_b32 a115, 0
	v_accvgpr_write_b32 a114, 0
	v_accvgpr_write_b32 a113, 0
	v_accvgpr_write_b32 a112, 0
	v_accvgpr_write_b32 a127, 0
	v_accvgpr_write_b32 a126, 0
	v_accvgpr_write_b32 a125, 0
	v_accvgpr_write_b32 a124, 0
	v_accvgpr_write_b32 a123, 0
	v_accvgpr_write_b32 a122, 0
	v_accvgpr_write_b32 a121, 0
	v_accvgpr_write_b32 a120, 0
	v_accvgpr_write_b32 a119, 0
	v_accvgpr_write_b32 a118, 0
	v_accvgpr_write_b32 a117, 0
	v_accvgpr_write_b32 a116, 0
	v_accvgpr_write_b32 a111, 0
	v_accvgpr_write_b32 a110, 0
	v_accvgpr_write_b32 a109, 0
	v_accvgpr_write_b32 a108, 0
	v_accvgpr_write_b32 a107, 0
	v_accvgpr_write_b32 a106, 0
	v_accvgpr_write_b32 a105, 0
	v_accvgpr_write_b32 a104, 0
	v_accvgpr_write_b32 a103, 0
	v_accvgpr_write_b32 a102, 0
	v_accvgpr_write_b32 a101, 0
	v_accvgpr_write_b32 a100, 0
	v_accvgpr_write_b32 a95, 0
	v_accvgpr_write_b32 a94, 0
	v_accvgpr_write_b32 a93, 0
	v_accvgpr_write_b32 a92, 0
	v_accvgpr_write_b32 a91, 0
	v_accvgpr_write_b32 a90, 0
	v_accvgpr_write_b32 a89, 0
	v_accvgpr_write_b32 a88, 0
	v_accvgpr_write_b32 a87, 0
	v_accvgpr_write_b32 a86, 0
	v_accvgpr_write_b32 a85, 0
	v_accvgpr_write_b32 a84, 0
	v_accvgpr_write_b32 a79, 0
	v_accvgpr_write_b32 a78, 0
	v_accvgpr_write_b32 a77, 0
	v_accvgpr_write_b32 a76, 0
	v_accvgpr_write_b32 a75, 0
	v_accvgpr_write_b32 a74, 0
	v_accvgpr_write_b32 a73, 0
	v_accvgpr_write_b32 a72, 0
	v_accvgpr_write_b32 a71, 0
	v_accvgpr_write_b32 a70, 0
	v_accvgpr_write_b32 a69, 0
	v_accvgpr_write_b32 a68, 0
	v_accvgpr_write_b32 a63, 0
	v_accvgpr_write_b32 a62, 0
	v_accvgpr_write_b32 a61, 0
	v_accvgpr_write_b32 a60, 0
	v_accvgpr_write_b32 a59, 0
	v_accvgpr_write_b32 a58, 0
	v_accvgpr_write_b32 a57, 0
	v_accvgpr_write_b32 a56, 0
	v_accvgpr_write_b32 a55, 0
	v_accvgpr_write_b32 a54, 0
	v_accvgpr_write_b32 a53, 0
	v_accvgpr_write_b32 a52, 0
	v_accvgpr_write_b32 a47, 0
	v_accvgpr_write_b32 a46, 0
	v_accvgpr_write_b32 a45, 0
	v_accvgpr_write_b32 a44, 0
	v_accvgpr_write_b32 a43, 0
	v_accvgpr_write_b32 a42, 0
	v_accvgpr_write_b32 a41, 0
	v_accvgpr_write_b32 a40, 0
	v_accvgpr_write_b32 a39, 0
	v_accvgpr_write_b32 a38, 0
	v_accvgpr_write_b32 a37, 0
	v_accvgpr_write_b32 a36, 0
	v_accvgpr_write_b32 a31, 0
	v_accvgpr_write_b32 a30, 0
	v_accvgpr_write_b32 a29, 0
	v_accvgpr_write_b32 a28, 0
	v_accvgpr_write_b32 a27, 0
	v_accvgpr_write_b32 a26, 0
	v_accvgpr_write_b32 a25, 0
	v_accvgpr_write_b32 a24, 0
	v_accvgpr_write_b32 a23, 0
	v_accvgpr_write_b32 a22, 0
	v_accvgpr_write_b32 a21, 0
	v_accvgpr_write_b32 a20, 0
	v_accvgpr_write_b32 a15, 0
	v_accvgpr_write_b32 a14, 0
	v_accvgpr_write_b32 a13, 0
	v_accvgpr_write_b32 a12, 0
	s_mov_b32 s5, 0
	s_mov_b64 s[6:7], 0
	s_mov_b32 s29, 0
	v_readfirstlane_b32 s100, v37
	s_waitcnt vmcnt(12)
	s_barrier
	s_add_u32 s101, s100, 0x18000
	s_add_u32 m0, s101, 0x0
	v_lshl_add_u64 v[14:15], v[76:77], 0, s[6:7]
	global_load_lds_dwordx4 v[14:15], off
	s_add_u32 m0, s101, 0x1000
	v_lshl_add_u64 v[14:15], v[74:75], 0, s[6:7]
	global_load_lds_dwordx4 v[14:15], off
	s_add_u32 m0, s101, 0x2000
	v_lshl_add_u64 v[14:15], v[72:73], 0, s[6:7]
	global_load_lds_dwordx4 v[14:15], off
	s_add_u32 m0, s101, 0x3000
	v_lshl_add_u64 v[14:15], v[70:71], 0, s[6:7]
	global_load_lds_dwordx4 v[14:15], off
	s_add_u32 m0, s101, 0x4000
	v_lshl_add_u64 v[14:15], v[68:69], 0, s[6:7]
	global_load_lds_dwordx4 v[14:15], off
	s_add_u32 m0, s101, 0x5000
	v_lshl_add_u64 v[14:15], v[66:67], 0, s[6:7]
	global_load_lds_dwordx4 v[14:15], off
	ds_read_b128 v[116:119], v35 offset:0
	ds_read_b128 v[120:123], v35 offset:2048
	ds_read_b128 v[124:127], v35 offset:4096
	ds_read_b128 v[128:131], v35 offset:6144
	ds_read_b128 v[84:87], v33 offset:0
	ds_read_b128 v[88:91], v33 offset:2048
	ds_read_b128 v[92:95], v33 offset:4096
	ds_read_b128 v[96:99], v33 offset:6144
	ds_read_b128 v[100:103], v33 offset:8192
	ds_read_b128 v[104:107], v33 offset:10240
	ds_read_b128 v[108:111], v33 offset:12288
	ds_read_b128 v[112:115], v33 offset:14336
; DI f4 mfma16(h8 a, h8 b, f4 c) { return __builtin_amdgcn_mfma_f32_16x16x32_f16(a, b, c, 0, 0, 0); }
; DI h8 lds128(unsigned a) { h8 r; asm volatile("ds_read_b128 %0, %1" : "=v"(r) : "v"(a)); return r; }
; DI void tie(h8& x) { asm volatile("" : "+v"(x)); }
; #define WAIT_LGKM(n) asm volatile("s_waitcnt lgkmcnt(" #n ")" ::: "memory")
; template <bool PRE = false, class AF, class BF>
; DI void gemm256(AF aptr, BF bptr, int nk, char* smem, f4 (&acc)[8][4]) {
;     ...
; #pragma unroll
;     for (int m = 0; m < 8; m++) a0[m] = lds128(base + offA + m * 2048);
; #pragma unroll
;     for (int n = 0; n < 4; n++) b0[n] = lds128(base + offB + n * 2048);
; #pragma unroll
;     for (int m = 0; m < 8; m++) a1[m] = lds128(base + (offA ^ 64) + m * 2048);
; #pragma unroll
;     for (int n = 0; n < 4; n++) b1[n] = lds128(base + (offB ^ 64) + n * 2048);
;     WAIT_LGKM(12);
; #pragma unroll
;     for (int m = 0; m < 8; m++) tie(a0[m]);
; #pragma unroll
;     for (int n = 0; n < 4; n++) tie(b0[n]);
; #pragma unroll
;     for (int m = 0; m < 8; m++)
; #pragma unroll
;       for (int n = 0; n < 4; n++) acc[m][n] = mfma16(a0[m], b0[n], acc[m][n]);
.Lg_e1_loop:
	s_mul_i32 s35, s29, 0xc000
	v_add_u32_e32 v8, s35, v39
	v_add_u32_e32 v9, s35, v41
	s_add_u32 s101, s29, 2
	s_sub_u32 s34, s101, 3
	s_cmp_lt_u32 s101, 3
	s_cselect_b32 s101, s101, s34
	s_mul_i32 s101, s101, 0xc000
	s_add_u32 s101, s101, s100
	s_cmp_lt_u32 s5, 14
	s_waitcnt lgkmcnt(0)
	s_cbranch_scc0 .Lg_e1_h1n
	v_mfma_f32_16x16x32_f16 a[0:3], v[84:87], v[116:119], a[0:3]
	ds_read_b128 a[200:203], v9 offset:0
	v_mfma_f32_16x16x32_f16 a[4:7], v[84:87], v[120:123], a[4:7]
	s_add_u32 m0, s101, 0x6000
	v_lshl_add_u64 v[14:15], v[64:65], 0, s[6:7]
	global_load_lds_dwordx4 v[14:15], off
	v_mfma_f32_16x16x32_f16 a[8:11], v[84:87], v[124:127], a[8:11]
	ds_read_b128 a[204:207], v9 offset:2048
	v_mfma_f32_16x16x32_f16 a[16:19], v[84:87], v[128:131], a[16:19]
	v_mfma_f32_16x16x32_f16 a[32:35], v[88:91], v[116:119], a[32:35]
	ds_read_b128 a[208:211], v9 offset:4096
	v_mfma_f32_16x16x32_f16 a[48:51], v[88:91], v[120:123], a[48:51]
	s_add_u32 m0, s101, 0x7000
	v_lshl_add_u64 v[14:15], v[62:63], 0, s[6:7]
	global_load_lds_dwordx4 v[14:15], off
	v_mfma_f32_16x16x32_f16 a[64:67], v[88:91], v[124:127], a[64:67]
	ds_read_b128 a[212:215], v9 offset:6144
	v_mfma_f32_16x16x32_f16 a[80:83], v[88:91], v[128:131], a[80:83]
	v_mfma_f32_16x16x32_f16 a[96:99], v[92:95], v[116:119], a[96:99]
	ds_read_b128 v[132:135], v8 offset:0
	v_mfma_f32_16x16x32_f16 a[112:115], v[92:95], v[120:123], a[112:115]
	v_lshl_add_u64 v[10:11], v[58:59], 0, s[6:7]
	s_add_u32 m0, s101, 0x8000
	v_lshl_add_u64 v[14:15], v[10:11], 0, s[74:75]
	global_load_lds_dwordx4 v[14:15], off
	v_mfma_f32_16x16x32_f16 a[124:127], v[92:95], v[124:127], a[124:127]
	ds_read_b128 v[136:139], v8 offset:2048
	v_mfma_f32_16x16x32_f16 a[120:123], v[92:95], v[128:131], a[120:123]
	v_mfma_f32_16x16x32_f16 a[116:119], v[96:99], v[116:119], a[116:119]
	ds_read_b128 v[0:3], v8 offset:4096
	v_mfma_f32_16x16x32_f16 a[108:111], v[96:99], v[120:123], a[108:111]
	v_lshl_add_u64 v[12:13], v[60:61], 0, s[6:7]
	s_add_u32 m0, s101, 0x9000
	v_lshl_add_u64 v[14:15], v[12:13], 0, s[74:75]
	global_load_lds_dwordx4 v[14:15], off
	v_mfma_f32_16x16x32_f16 a[104:107], v[96:99], v[124:127], a[104:107]
	ds_read_b128 v[4:7], v8 offset:6144
	v_mfma_f32_16x16x32_f16 a[100:103], v[96:99], v[128:131], a[100:103]
	v_mfma_f32_16x16x32_f16 a[92:95], v[100:103], v[116:119], a[92:95]
	ds_read_b128 v[144:147], v8 offset:8192
	v_mfma_f32_16x16x32_f16 a[88:91], v[100:103], v[120:123], a[88:91]
	s_add_u32 m0, s101, 0xa000
	v_lshl_add_u64 v[14:15], v[10:11], 0, s[76:77]
	global_load_lds_dwordx4 v[14:15], off
	v_mfma_f32_16x16x32_f16 a[84:87], v[100:103], v[124:127], a[84:87]
	ds_read_b128 v[140:143], v8 offset:10240
	v_mfma_f32_16x16x32_f16 a[76:79], v[100:103], v[128:131], a[76:79]
	v_mfma_f32_16x16x32_f16 a[72:75], v[104:107], v[116:119], a[72:75]
	ds_read_b128 v[150:153], v8 offset:12288
	v_mfma_f32_16x16x32_f16 a[68:71], v[104:107], v[120:123], a[68:71]
	s_add_u32 m0, s101, 0xb000
	v_lshl_add_u64 v[14:15], v[12:13], 0, s[76:77]
	global_load_lds_dwordx4 v[14:15], off
	v_mfma_f32_16x16x32_f16 a[60:63], v[104:107], v[124:127], a[60:63]
	ds_read_b128 v[154:157], v8 offset:14336
	v_mfma_f32_16x16x32_f16 a[56:59], v[104:107], v[128:131], a[56:59]
	v_mfma_f32_16x16x32_f16 a[52:55], v[108:111], v[116:119], a[52:55]
	v_mfma_f32_16x16x32_f16 a[44:47], v[108:111], v[120:123], a[44:47]
	s_add_u32 s34, s29, 1
	v_mfma_f32_16x16x32_f16 a[40:43], v[108:111], v[124:127], a[40:43]
	s_cmp_eq_u32 s34, 3
	v_mfma_f32_16x16x32_f16 a[36:39], v[108:111], v[128:131], a[36:39]
	s_cselect_b32 s34, 0, s34
	v_mfma_f32_16x16x32_f16 a[28:31], v[112:115], v[116:119], a[28:31]
	s_mul_i32 s35, s34, 0xc000
	v_mfma_f32_16x16x32_f16 a[24:27], v[112:115], v[120:123], a[24:27]
	v_add_u32_e32 v22, s35, v33
	v_mfma_f32_16x16x32_f16 a[20:23], v[112:115], v[124:127], a[20:23]
	v_add_u32_e32 v23, s35, v35
	v_mfma_f32_16x16x32_f16 a[12:15], v[112:115], v[128:131], a[12:15]
	s_branch .Lg_e1_mid
.Lg_e1_h1n:
	v_mfma_f32_16x16x32_f16 a[0:3], v[84:87], v[116:119], a[0:3]
	ds_read_b128 a[200:203], v9 offset:0
	v_mfma_f32_16x16x32_f16 a[4:7], v[84:87], v[120:123], a[4:7]
	v_mfma_f32_16x16x32_f16 a[8:11], v[84:87], v[124:127], a[8:11]
	ds_read_b128 a[204:207], v9 offset:2048
	v_mfma_f32_16x16x32_f16 a[16:19], v[84:87], v[128:131], a[16:19]
	v_mfma_f32_16x16x32_f16 a[32:35], v[88:91], v[116:119], a[32:35]
	ds_read_b128 a[208:211], v9 offset:4096
	v_mfma_f32_16x16x32_f16 a[48:51], v[88:91], v[120:123], a[48:51]
	v_mfma_f32_16x16x32_f16 a[64:67], v[88:91], v[124:127], a[64:67]
	ds_read_b128 a[212:215], v9 offset:6144
	v_mfma_f32_16x16x32_f16 a[80:83], v[88:91], v[128:131], a[80:83]
	v_mfma_f32_16x16x32_f16 a[96:99], v[92:95], v[116:119], a[96:99]
	ds_read_b128 v[132:135], v8 offset:0
	v_mfma_f32_16x16x32_f16 a[112:115], v[92:95], v[120:123], a[112:115]
	v_mfma_f32_16x16x32_f16 a[124:127], v[92:95], v[124:127], a[124:127]
	ds_read_b128 v[136:139], v8 offset:2048
	v_mfma_f32_16x16x32_f16 a[120:123], v[92:95], v[128:131], a[120:123]
	v_mfma_f32_16x16x32_f16 a[116:119], v[96:99], v[116:119], a[116:119]
	ds_read_b128 v[0:3], v8 offset:4096
	v_mfma_f32_16x16x32_f16 a[108:111], v[96:99], v[120:123], a[108:111]
	v_mfma_f32_16x16x32_f16 a[104:107], v[96:99], v[124:127], a[104:107]
	ds_read_b128 v[4:7], v8 offset:6144
	v_mfma_f32_16x16x32_f16 a[100:103], v[96:99], v[128:131], a[100:103]
	v_mfma_f32_16x16x32_f16 a[92:95], v[100:103], v[116:119], a[92:95]
	ds_read_b128 v[144:147], v8 offset:8192
	v_mfma_f32_16x16x32_f16 a[88:91], v[100:103], v[120:123], a[88:91]
	v_mfma_f32_16x16x32_f16 a[84:87], v[100:103], v[124:127], a[84:87]
	ds_read_b128 v[140:143], v8 offset:10240
	v_mfma_f32_16x16x32_f16 a[76:79], v[100:103], v[128:131], a[76:79]
	v_mfma_f32_16x16x32_f16 a[72:75], v[104:107], v[116:119], a[72:75]
	ds_read_b128 v[150:153], v8 offset:12288
	v_mfma_f32_16x16x32_f16 a[68:71], v[104:107], v[120:123], a[68:71]
	v_mfma_f32_16x16x32_f16 a[60:63], v[104:107], v[124:127], a[60:63]
	ds_read_b128 v[154:157], v8 offset:14336
	v_mfma_f32_16x16x32_f16 a[56:59], v[104:107], v[128:131], a[56:59]
	v_mfma_f32_16x16x32_f16 a[52:55], v[108:111], v[116:119], a[52:55]
	v_mfma_f32_16x16x32_f16 a[44:47], v[108:111], v[120:123], a[44:47]
	s_add_u32 s34, s29, 1
	v_mfma_f32_16x16x32_f16 a[40:43], v[108:111], v[124:127], a[40:43]
	s_cmp_eq_u32 s34, 3
	v_mfma_f32_16x16x32_f16 a[36:39], v[108:111], v[128:131], a[36:39]
	s_cselect_b32 s34, 0, s34
	v_mfma_f32_16x16x32_f16 a[28:31], v[112:115], v[116:119], a[28:31]
	s_mul_i32 s35, s34, 0xc000
	v_mfma_f32_16x16x32_f16 a[24:27], v[112:115], v[120:123], a[24:27]
	v_add_u32_e32 v22, s35, v33
	v_mfma_f32_16x16x32_f16 a[20:23], v[112:115], v[124:127], a[20:23]
	v_add_u32_e32 v23, s35, v35
	v_mfma_f32_16x16x32_f16 a[12:15], v[112:115], v[128:131], a[12:15]
.Lg_e1_mid:
	s_cmp_eq_u32 s5, 15
	s_cbranch_scc1 .Lg_e1_last
	s_cmp_lt_u32 s5, 14
	s_cbranch_scc1 .Lg_e1_w12
	s_waitcnt vmcnt(0) lgkmcnt(0)
	s_branch .Lg_e1_wd

; DI f4 mfma16(h8 a, h8 b, f4 c) { return __builtin_amdgcn_mfma_f32_16x16x32_f16(a, b, c, 0, 0, 0); }
; DI h8 lds128(unsigned a) { h8 r; asm volatile("ds_read_b128 %0, %1" : "=v"(r) : "v"(a)); return r; }
; DI void tie(h8& x) { asm volatile("" : "+v"(x)); }
; #define WAIT_LGKM(n) asm volatile("s_waitcnt lgkmcnt(" #n ")" ::: "memory")
; template <bool PRE = false, class AF, class BF>
; DI void gemm256(AF aptr, BF bptr, int nk, char* smem, f4 (&acc)[8][4]) {
;     ...
;     if (kt + 2 < nk) issue(kt + 2, st == 0 ? 2 : st - 1);
;     const unsigned base = sbase + st * 49152;
;     st = st == 2 ? 0 : st + 1;
;     h8 a0[8], b0[4], a1[8], b1[4];
; #pragma unroll
;     for (int m = 0; m < 8; m++) a0[m] = lds128(base + offA + m * 2048);
; #pragma unroll
;     for (int n = 0; n < 4; n++) b0[n] = lds128(base + offB + n * 2048);
; #pragma unroll
;     for (int m = 0; m < 8; m++) a1[m] = lds128(base + (offA ^ 64) + m * 2048);
; #pragma unroll
;     for (int n = 0; n < 4; n++) b1[n] = lds128(base + (offB ^ 64) + n * 2048);
;     WAIT_LGKM(12);
; #pragma unroll
;     for (int m = 0; m < 8; m++) tie(a0[m]);
; #pragma unroll
;     for (int n = 0; n < 4; n++) tie(b0[n]);
; #pragma unroll
;     for (int m = 0; m < 8; m++)
; #pragma unroll
;       for (int n = 0; n < 4; n++) acc[m][n] = mfma16(a0[m], b0[n], acc[m][n]);
;     WAIT_LGKM(0);
; #pragma unroll
;     for (int m = 0; m < 8; m++) tie(a1[m]);
; #pragma unroll
;     for (int n = 0; n < 4; n++) tie(b1[n]);
; #pragma unroll
;     for (int m = 0; m < 8; m++)
; #pragma unroll
;       for (int n = 0; n < 4; n++) acc[m][n] = mfma16(a1[m], b1[n], acc[m][n]);
.Lg_e1_wd:
	s_barrier
	s_add_u32 s6, s6, 0x80
	s_addc_u32 s7, s7, 0
	s_mul_i32 s101, s29, 0xc000
	s_add_u32 s101, s101, s100
	s_cmp_lt_u32 s5, 13
	s_cbranch_scc0 .Lg_e1_noissue
	v_mfma_f32_16x16x32_f16 a[0:3], v[132:135], a[200:203], a[0:3]
	ds_read_b128 v[116:119], v23 offset:0
	v_mfma_f32_16x16x32_f16 a[4:7], v[132:135], a[204:207], a[4:7]
	s_add_u32 m0, s101, 0x0
	v_lshl_add_u64 v[14:15], v[76:77], 0, s[6:7]
	global_load_lds_dwordx4 v[14:15], off
	v_mfma_f32_16x16x32_f16 a[8:11], v[132:135], a[208:211], a[8:11]
	ds_read_b128 v[120:123], v23 offset:2048
	v_mfma_f32_16x16x32_f16 a[16:19], v[132:135], a[212:215], a[16:19]
	v_mfma_f32_16x16x32_f16 a[32:35], v[136:139], a[200:203], a[32:35]
	ds_read_b128 v[124:127], v23 offset:4096
	v_mfma_f32_16x16x32_f16 a[48:51], v[136:139], a[204:207], a[48:51]
	s_add_u32 m0, s101, 0x1000
	v_lshl_add_u64 v[14:15], v[74:75], 0, s[6:7]
	global_load_lds_dwordx4 v[14:15], off
	v_mfma_f32_16x16x32_f16 a[64:67], v[136:139], a[208:211], a[64:67]
	ds_read_b128 v[128:131], v23 offset:6144
	v_mfma_f32_16x16x32_f16 a[80:83], v[136:139], a[212:215], a[80:83]
	v_mfma_f32_16x16x32_f16 a[96:99], v[0:3], a[200:203], a[96:99]
	ds_read_b128 v[84:87], v22 offset:0
	v_mfma_f32_16x16x32_f16 a[112:115], v[0:3], a[204:207], a[112:115]
	s_add_u32 m0, s101, 0x2000
	v_lshl_add_u64 v[14:15], v[72:73], 0, s[6:7]
	global_load_lds_dwordx4 v[14:15], off
	v_mfma_f32_16x16x32_f16 a[124:127], v[0:3], a[208:211], a[124:127]
	ds_read_b128 v[88:91], v22 offset:2048
	v_mfma_f32_16x16x32_f16 a[120:123], v[0:3], a[212:215], a[120:123]
	v_mfma_f32_16x16x32_f16 a[116:119], v[4:7], a[200:203], a[116:119]
	ds_read_b128 v[92:95], v22 offset:4096
	v_mfma_f32_16x16x32_f16 a[108:111], v[4:7], a[204:207], a[108:111]
	s_add_u32 m0, s101, 0x3000
	v_lshl_add_u64 v[14:15], v[70:71], 0, s[6:7]
	global_load_lds_dwordx4 v[14:15], off
	v_mfma_f32_16x16x32_f16 a[104:107], v[4:7], a[208:211], a[104:107]
	ds_read_b128 v[96:99], v22 offset:6144
	v_mfma_f32_16x16x32_f16 a[100:103], v[4:7], a[212:215], a[100:103]
	v_mfma_f32_16x16x32_f16 a[92:95], v[144:147], a[200:203], a[92:95]
	ds_read_b128 v[100:103], v22 offset:8192
	v_mfma_f32_16x16x32_f16 a[88:91], v[144:147], a[204:207], a[88:91]
	s_add_u32 m0, s101, 0x4000
	v_lshl_add_u64 v[14:15], v[68:69], 0, s[6:7]
	global_load_lds_dwordx4 v[14:15], off
	v_mfma_f32_16x16x32_f16 a[84:87], v[144:147], a[208:211], a[84:87]
	ds_read_b128 v[104:107], v22 offset:10240
	v_mfma_f32_16x16x32_f16 a[76:79], v[144:147], a[212:215], a[76:79]
	v_mfma_f32_16x16x32_f16 a[72:75], v[140:143], a[200:203], a[72:75]
	ds_read_b128 v[108:111], v22 offset:12288
	v_mfma_f32_16x16x32_f16 a[68:71], v[140:143], a[204:207], a[68:71]
	s_add_u32 m0, s101, 0x5000
	v_lshl_add_u64 v[14:15], v[66:67], 0, s[6:7]
	global_load_lds_dwordx4 v[14:15], off
	v_mfma_f32_16x16x32_f16 a[60:63], v[140:143], a[208:211], a[60:63]
	ds_read_b128 v[112:115], v22 offset:14336
	v_mfma_f32_16x16x32_f16 a[56:59], v[140:143], a[212:215], a[56:59]
	v_mfma_f32_16x16x32_f16 a[52:55], v[150:153], a[200:203], a[52:55]
	v_mfma_f32_16x16x32_f16 a[44:47], v[150:153], a[204:207], a[44:47]
	v_mfma_f32_16x16x32_f16 a[40:43], v[150:153], a[208:211], a[40:43]
	v_mfma_f32_16x16x32_f16 a[36:39], v[150:153], a[212:215], a[36:39]
	v_mfma_f32_16x16x32_f16 a[28:31], v[154:157], a[200:203], a[28:31]
	v_mfma_f32_16x16x32_f16 a[24:27], v[154:157], a[204:207], a[24:27]
	v_mfma_f32_16x16x32_f16 a[20:23], v[154:157], a[208:211], a[20:23]
	v_mfma_f32_16x16x32_f16 a[12:15], v[154:157], a[212:215], a[12:15]
	s_branch .Lg_e1_next
.Lg_e1_noissue:
	v_mfma_f32_16x16x32_f16 a[0:3], v[132:135], a[200:203], a[0:3]
	ds_read_b128 v[116:119], v23 offset:0
	v_mfma_f32_16x16x32_f16 a[4:7], v[132:135], a[204:207], a[4:7]
	v_mfma_f32_16x16x32_f16 a[8:11], v[132:135], a[208:211], a[8:11]
	ds_read_b128 v[120:123], v23 offset:2048
	v_mfma_f32_16x16x32_f16 a[16:19], v[132:135], a[212:215], a[16:19]
	v_mfma_f32_16x16x32_f16 a[32:35], v[136:139], a[200:203], a[32:35]
	ds_read_b128 v[124:127], v23 offset:4096
	v_mfma_f32_16x16x32_f16 a[48:51], v[136:139], a[204:207], a[48:51]
	v_mfma_f32_16x16x32_f16 a[64:67], v[136:139], a[208:211], a[64:67]
	ds_read_b128 v[128:131], v23 offset:6144
	v_mfma_f32_16x16x32_f16 a[80:83], v[136:139], a[212:215], a[80:83]
	v_mfma_f32_16x16x32_f16 a[96:99], v[0:3], a[200:203], a[96:99]
	ds_read_b128 v[84:87], v22 offset:0
	v_mfma_f32_16x16x32_f16 a[112:115], v[0:3], a[204:207], a[112:115]
	v_mfma_f32_16x16x32_f16 a[124:127], v[0:3], a[208:211], a[124:127]
	ds_read_b128 v[88:91], v22 offset:2048
	v_mfma_f32_16x16x32_f16 a[120:123], v[0:3], a[212:215], a[120:123]
	v_mfma_f32_16x16x32_f16 a[116:119], v[4:7], a[200:203], a[116:119]
	ds_read_b128 v[92:95], v22 offset:4096
	v_mfma_f32_16x16x32_f16 a[108:111], v[4:7], a[204:207], a[108:111]
	v_mfma_f32_16x16x32_f16 a[104:107], v[4:7], a[208:211], a[104:107]
	ds_read_b128 v[96:99], v22 offset:6144
	v_mfma_f32_16x16x32_f16 a[100:103], v[4:7], a[212:215], a[100:103]
	v_mfma_f32_16x16x32_f16 a[92:95], v[144:147], a[200:203], a[92:95]
	ds_read_b128 v[100:103], v22 offset:8192
	v_mfma_f32_16x16x32_f16 a[88:91], v[144:147], a[204:207], a[88:91]
	v_mfma_f32_16x16x32_f16 a[84:87], v[144:147], a[208:211], a[84:87]
	ds_read_b128 v[104:107], v22 offset:10240
	v_mfma_f32_16x16x32_f16 a[76:79], v[144:147], a[212:215], a[76:79]
	v_mfma_f32_16x16x32_f16 a[72:75], v[140:143], a[200:203], a[72:75]
	ds_read_b128 v[108:111], v22 offset:12288
	v_mfma_f32_16x16x32_f16 a[68:71], v[140:143], a[204:207], a[68:71]
	v_mfma_f32_16x16x32_f16 a[60:63], v[140:143], a[208:211], a[60:63]
	ds_read_b128 v[112:115], v22 offset:14336
	v_mfma_f32_16x16x32_f16 a[56:59], v[140:143], a[212:215], a[56:59]
	v_mfma_f32_16x16x32_f16 a[52:55], v[150:153], a[200:203], a[52:55]
	v_mfma_f32_16x16x32_f16 a[44:47], v[150:153], a[204:207], a[44:47]
	v_mfma_f32_16x16x32_f16 a[40:43], v[150:153], a[208:211], a[40:43]
	v_mfma_f32_16x16x32_f16 a[36:39], v[150:153], a[212:215], a[36:39]
	v_mfma_f32_16x16x32_f16 a[28:31], v[154:157], a[200:203], a[28:31]
	v_mfma_f32_16x16x32_f16 a[24:27], v[154:157], a[204:207], a[24:27]
	v_mfma_f32_16x16x32_f16 a[20:23], v[154:157], a[208:211], a[20:23]
	v_mfma_f32_16x16x32_f16 a[12:15], v[154:157], a[212:215], a[12:15]
.Lg_e1_next:
	s_mov_b32 s29, s34
	s_add_u32 s5, s5, 1
	s_branch .Lg_e1_loop

; DI void moe_e2_phase(const Params& P, int l, char* smem, int* tb) {
;     ...
;     int e = 0;
;     while (tb[e + 1] <= rt) e++;
;     const int rl = rt - tb[e], cnt = P.cnt[l * 32 + e];
;     const int* lst = P.list + (size_t)e * LCAP; const float* lstw = P.listW + (size_t)e * LCAP;
;     int aa[2][8]; float ww[2][8];
; #pragma unroll
;     for (int h = 0; h < 2; h++)
; #pragma unroll
;       for (int i = 0; i < 8; i++) {
;         const int idx = rl * 256 + wr2 * 128 + h * 64 + ((i * 64 + lane2) >> 3);
;         const int ic = min(idx, cnt - 1);
;         const int av = lst[ic]; const float wv = lstw[ic];
;         aa[h][i] = idx < cnt ? av : -1; ww[h][i] = wv;
;       }
.LBB0_612:
	v_mov_b32_e32 v0, s2
	ds_read_b32 v0, v0 offset:8
	s_add_i32 s1, s1, 1
	s_add_i32 s2, s2, 4
	s_waitcnt lgkmcnt(0)
	v_cmp_ge_i32_e32 vcc, s0, v0
	s_cbranch_vccnz .LBB0_612
	s_add_i32 s84, s1, s20
	v_mov_b32_e32 v0, s2
	s_lshl_b64 s[2:3], s[84:85], 2
	v_readlane_b32 s4, v253, 63
	v_readlane_b32 s5, v255, 0
	s_add_u32 s2, s4, s2
	s_addc_u32 s3, s5, s3
	global_load_dword v33, v149, s[2:3]
	ds_read_b32 v0, v0
	v_and_b32_e32 v1, 0xffffff80, v87
	s_mul_hi_u32 s3, s1, 0x84000
	s_mul_i32 s1, s1, 0x84000
	v_readlane_b32 s4, v255, 24
	s_waitcnt lgkmcnt(0)
	v_sub_u32_e32 v0, s0, v0
	v_lshl_add_u32 v1, v0, 8, v1
	v_bfe_u32 v86, v87, 3, 3
	v_readlane_b32 s5, v255, 25
	s_add_u32 s4, s4, s1
	v_or_b32_e32 v88, v1, v86
	s_addc_u32 s5, s5, s3
	v_readlane_b32 s22, v254, 0
	v_readlane_b32 s23, v254, 1
	s_add_u32 s2, s22, s1
	s_addc_u32 s3, s23, s3
	v_or_b32_e32 v83, 8, v86
	v_or_b32_e32 v84, v1, v83
	v_or_b32_e32 v80, 16, v86
	v_or_b32_e32 v81, v1, v80
	v_or_b32_e32 v77, 24, v86
	v_or_b32_e32 v78, v1, v77
	v_or_b32_e32 v74, 32, v86
	v_or_b32_e32 v75, v1, v74
	v_or_b32_e32 v69, 40, v86
	v_or_b32_e32 v70, v1, v69
	v_or_b32_e32 v66, 48, v86
	v_or_b32_e32 v67, v1, v66
	v_or_b32_e32 v63, 56, v86
	v_or_b32_e32 v64, v1, v63
	v_or_b32_e32 v1, 64, v1
	v_or_b32_e32 v72, v1, v86
	v_or_b32_e32 v59, v1, v83
	v_or_b32_e32 v55, v1, v80
	v_or_b32_e32 v51, v1, v77
	v_or_b32_e32 v47, v1, v74
	v_or_b32_e32 v43, v1, v69
	v_or_b32_e32 v39, v1, v66
	v_or_b32_e32 v35, v1, v63
	s_mov_b32 s1, 0x8040
	v_accvgpr_write_b32 a3, 0
	v_accvgpr_write_b32 a2, 0
	v_accvgpr_write_b32 a1, 0
	v_accvgpr_write_b32 a0, 0
	v_accvgpr_write_b32 a7, 0
	v_accvgpr_write_b32 a6, 0
	v_accvgpr_write_b32 a5, 0
	v_accvgpr_write_b32 a4, 0
	v_accvgpr_write_b32 a11, 0
	v_accvgpr_write_b32 a10, 0
	v_accvgpr_write_b32 a9, 0
	v_accvgpr_write_b32 a8, 0
	v_accvgpr_write_b32 a19, 0
	v_accvgpr_write_b32 a18, 0
	v_accvgpr_write_b32 a17, 0
	v_accvgpr_write_b32 a16, 0
	v_accvgpr_write_b32 a35, 0
	v_accvgpr_write_b32 a34, 0
	v_accvgpr_write_b32 a33, 0
	v_accvgpr_write_b32 a32, 0
	v_accvgpr_write_b32 a51, 0
	v_accvgpr_write_b32 a50, 0
	v_accvgpr_write_b32 a49, 0
	v_accvgpr_write_b32 a48, 0
	v_accvgpr_write_b32 a67, 0
	v_accvgpr_write_b32 a66, 0
	v_accvgpr_write_b32 a65, 0
	v_accvgpr_write_b32 a64, 0
	v_accvgpr_write_b32 a83, 0
	v_accvgpr_write_b32 a82, 0
	v_accvgpr_write_b32 a81, 0
	v_accvgpr_write_b32 a80, 0
	v_accvgpr_write_b32 a99, 0
	v_accvgpr_write_b32 a98, 0
	v_accvgpr_write_b32 a97, 0
	v_accvgpr_write_b32 a96, 0
	v_accvgpr_write_b32 a115, 0
	v_accvgpr_write_b32 a114, 0
	v_accvgpr_write_b32 a113, 0
	s_waitcnt vmcnt(0)
	v_add_u32_e32 v0, -1, v33
	v_min_i32_e32 v2, v88, v0
	v_ashrrev_i32_e32 v3, 31, v2
	v_lshlrev_b64 v[2:3], 2, v[2:3]
	v_lshl_add_u64 v[4:5], s[4:5], 0, v[2:3]
	v_lshl_add_u64 v[2:3], s[2:3], 0, v[2:3]
	global_load_dword v89, v[4:5], off
	global_load_dword v62, v[2:3], off
	v_min_i32_e32 v2, v84, v0
	v_ashrrev_i32_e32 v3, 31, v2
	v_lshlrev_b64 v[2:3], 2, v[2:3]
	v_lshl_add_u64 v[4:5], s[4:5], 0, v[2:3]
	v_lshl_add_u64 v[2:3], s[2:3], 0, v[2:3]
	global_load_dword v85, v[4:5], off
	global_load_dword v60, v[2:3], off
	v_min_i32_e32 v2, v81, v0
	v_ashrrev_i32_e32 v3, 31, v2
	v_lshlrev_b64 v[2:3], 2, v[2:3]
	v_lshl_add_u64 v[4:5], s[4:5], 0, v[2:3]
	v_lshl_add_u64 v[2:3], s[2:3], 0, v[2:3]
	global_load_dword v82, v[4:5], off
	global_load_dword v58, v[2:3], off
	v_min_i32_e32 v2, v78, v0
	v_ashrrev_i32_e32 v3, 31, v2
	v_lshlrev_b64 v[2:3], 2, v[2:3]
	v_lshl_add_u64 v[4:5], s[4:5], 0, v[2:3]
	v_lshl_add_u64 v[2:3], s[2:3], 0, v[2:3]
	global_load_dword v79, v[4:5], off
	global_load_dword v56, v[2:3], off
	v_min_i32_e32 v2, v75, v0
	v_ashrrev_i32_e32 v3, 31, v2
	v_lshlrev_b64 v[2:3], 2, v[2:3]
	v_lshl_add_u64 v[4:5], s[4:5], 0, v[2:3]
	v_lshl_add_u64 v[2:3], s[2:3], 0, v[2:3]
	global_load_dword v76, v[4:5], off
	global_load_dword v54, v[2:3], off
	v_min_i32_e32 v2, v70, v0
	v_ashrrev_i32_e32 v3, 31, v2
	v_lshlrev_b64 v[2:3], 2, v[2:3]
	v_lshl_add_u64 v[4:5], s[4:5], 0, v[2:3]
	v_lshl_add_u64 v[2:3], s[2:3], 0, v[2:3]
	global_load_dword v71, v[4:5], off
	global_load_dword v52, v[2:3], off
	v_min_i32_e32 v2, v67, v0
	v_ashrrev_i32_e32 v3, 31, v2
	v_lshlrev_b64 v[2:3], 2, v[2:3]
	v_lshl_add_u64 v[4:5], s[4:5], 0, v[2:3]
	v_lshl_add_u64 v[2:3], s[2:3], 0, v[2:3]
	global_load_dword v68, v[4:5], off
	global_load_dword v50, v[2:3], off
	v_min_i32_e32 v2, v64, v0
	v_ashrrev_i32_e32 v3, 31, v2
	v_lshlrev_b64 v[2:3], 2, v[2:3]
	v_lshl_add_u64 v[4:5], s[4:5], 0, v[2:3]
	v_lshl_add_u64 v[2:3], s[2:3], 0, v[2:3]
	global_load_dword v65, v[4:5], off
	global_load_dword v48, v[2:3], off
	v_min_i32_e32 v2, v72, v0
	v_ashrrev_i32_e32 v3, 31, v2
	v_lshlrev_b64 v[2:3], 2, v[2:3]
	v_lshl_add_u64 v[4:5], s[4:5], 0, v[2:3]
	v_lshl_add_u64 v[2:3], s[2:3], 0, v[2:3]
	global_load_dword v73, v[4:5], off
	global_load_dword v46, v[2:3], off
	v_min_i32_e32 v2, v59, v0
	v_ashrrev_i32_e32 v3, 31, v2
	v_lshlrev_b64 v[2:3], 2, v[2:3]
	v_lshl_add_u64 v[4:5], s[4:5], 0, v[2:3]
	v_lshl_add_u64 v[2:3], s[2:3], 0, v[2:3]
	global_load_dword v61, v[4:5], off
	global_load_dword v44, v[2:3], off
	v_min_i32_e32 v2, v55, v0
	v_ashrrev_i32_e32 v3, 31, v2
	v_lshlrev_b64 v[2:3], 2, v[2:3]
	v_lshl_add_u64 v[4:5], s[4:5], 0, v[2:3]
	v_lshl_add_u64 v[2:3], s[2:3], 0, v[2:3]
	global_load_dword v57, v[4:5], off
	global_load_dword v42, v[2:3], off
	v_min_i32_e32 v2, v51, v0
	v_ashrrev_i32_e32 v3, 31, v2
	v_lshlrev_b64 v[2:3], 2, v[2:3]
	v_lshl_add_u64 v[4:5], s[4:5], 0, v[2:3]
	v_lshl_add_u64 v[2:3], s[2:3], 0, v[2:3]
	global_load_dword v53, v[4:5], off
	global_load_dword v40, v[2:3], off
	v_min_i32_e32 v2, v47, v0
	v_ashrrev_i32_e32 v3, 31, v2
; #define TIDX tid_opaque()
; DI void wait_vm0() { asm volatile("s_waitcnt vmcnt(0)" ::: "memory"); }
; DI h8 lds128(unsigned a) { h8 r; asm volatile("ds_read_b128 %0, %1" : "=v"(r) : "v"(a)); return r; }
; DI unsigned lds_addr(const void* p) { return (unsigned)(size_t)p; }
; DI void raw_barrier() { asm volatile("" ::: "memory"); __builtin_amdgcn_s_barrier(); asm volatile("" ::: "memory"); }
; template <bool PRE = false, class AF, class BF>
; DI void gemm256(AF aptr, BF bptr, int nk, char* smem, f4 (&acc)[8][4]) {
;   const int tid = TIDX, lane = tid & 63, wave = tid >> 6, fr = lane & 15, fq = lane >> 4, wr = wave >> 1, wc = wave & 1;
; #pragma unroll
;   for (int m = 0; m < 8; m++)
; #pragma unroll
;     for (int n = 0; n < 4; n++) acc[m][n] = (f4){0.f, 0.f, 0.f, 0.f};
;   auto issue = [&](int kt, int st) {
;     char* d = smem + st * 49152 + tid * 16;
; #pragma unroll
;     for (int i = 0; i < 8; i++) glds16(aptr(i) + kt * 64, d + i * 4096);
; #pragma unroll
;     for (int i = 0; i < 4; i++) glds16(bptr(i) + kt * 64, d + 32768 + i * 4096);
;   };
;   const unsigned sw = (unsigned)((fq ^ (fr >> 1)) << 4);
;   const unsigned offA = (wr * 128 + fr) * 128 + sw, offB = 32768 + (wc * 64 + fr) * 128 + sw;
;   const unsigned sbase = lds_addr(smem);
;   if (!PRE) { issue(0, 0); if (nk > 1) issue(1, 1); }
;   int st = 0;
; #pragma unroll 1
;   for (int kt = 0; kt < nk; kt++) {
;     if (kt + 1 < nk) asm volatile("s_waitcnt vmcnt(12)" ::: "memory"); else wait_vm0();
;     raw_barrier();
;     if (kt + 2 < nk) issue(kt + 2, st == 0 ? 2 : st - 1);
;     const unsigned base = sbase + st * 49152;
;     st = st == 2 ? 0 : st + 1;
;     h8 a0[8], b0[4], a1[8], b1[4];
; #pragma unroll
;     for (int m = 0; m < 8; m++) a0[m] = lds128(base + offA + m * 2048);
; #pragma unroll
;     for (int n = 0; n < 4; n++) b0[n] = lds128(base + offB + n * 2048);
; DI void moe_e2_phase(const Params& P, int l, char* smem, int* tb) {
;     ...
;         const int idx = rl * 256 + wr2 * 128 + h * 64 + ((i * 64 + lane2) >> 3);
;         const int ic = min(idx, cnt - 1);
;         const int av = lst[ic]; const float wv = lstw[ic];
;         aa[h][i] = idx < cnt ? av : -1; ww[h][i] = wv;
	v_lshlrev_b64 v[2:3], 2, v[2:3]
	v_lshl_add_u64 v[4:5], s[4:5], 0, v[2:3]
	v_lshl_add_u64 v[2:3], s[2:3], 0, v[2:3]
	global_load_dword v49, v[4:5], off
	global_load_dword v38, v[2:3], off
	v_min_i32_e32 v2, v43, v0
	v_ashrrev_i32_e32 v3, 31, v2
	v_lshlrev_b64 v[2:3], 2, v[2:3]
	v_lshl_add_u64 v[4:5], s[4:5], 0, v[2:3]
	v_lshl_add_u64 v[2:3], s[2:3], 0, v[2:3]
	global_load_dword v45, v[4:5], off
	global_load_dword v36, v[2:3], off
	v_min_i32_e32 v2, v39, v0
	v_ashrrev_i32_e32 v3, 31, v2
	v_min_i32_e32 v0, v35, v0
	v_lshlrev_b64 v[2:3], 2, v[2:3]
	v_ashrrev_i32_e32 v1, 31, v0
	v_lshl_add_u64 v[4:5], s[4:5], 0, v[2:3]
	v_lshl_add_u64 v[2:3], s[2:3], 0, v[2:3]
	v_lshlrev_b64 v[0:1], 2, v[0:1]
	global_load_dword v41, v[4:5], off
	global_load_dword v34, v[2:3], off
	v_lshl_add_u64 v[2:3], s[4:5], 0, v[0:1]
	v_lshl_add_u64 v[0:1], s[2:3], 0, v[0:1]
	global_load_dword v37, v[2:3], off
	global_load_dword v32, v[0:1], off
	v_mov_b32_e32 v0, v172
	v_accvgpr_write_b32 a112, 0
	v_lshlrev_b32_e32 v1, 3, v0
	v_and_b32_e32 v2, 48, v0
	v_bitop3_b32 v1, v1, v2, s37 bitop3:0x6c
	v_lshlrev_b32_e32 v2, 7, v0
	v_and_b32_e32 v3, 0xffffc780, v2
	v_and_b32_e32 v2, 0x2780, v2
	v_or_b32_e32 v4, v1, v2
	v_or_b32_e32 v156, v1, v3
	v_or_b32_e32 v157, 0x8000, v4
	v_lshlrev_b32_e32 v158, 4, v0
	v_bitop3_b32 v159, v1, 64, v3 bitop3:0x36
	v_bitop3_b32 v160, v1, s1, v2 bitop3:0x36
	v_accvgpr_write_b32 a127, 0
	v_accvgpr_write_b32 a126, 0
	v_accvgpr_write_b32 a125, 0
	v_accvgpr_write_b32 a124, 0
	v_accvgpr_write_b32 a123, 0
	v_accvgpr_write_b32 a122, 0
	v_accvgpr_write_b32 a121, 0
	v_accvgpr_write_b32 a120, 0
	v_accvgpr_write_b32 a119, 0
	v_accvgpr_write_b32 a118, 0
	v_accvgpr_write_b32 a117, 0
	v_accvgpr_write_b32 a116, 0
	v_accvgpr_write_b32 a111, 0
	v_accvgpr_write_b32 a110, 0
	v_accvgpr_write_b32 a109, 0
	v_accvgpr_write_b32 a108, 0
	v_accvgpr_write_b32 a107, 0
	v_accvgpr_write_b32 a106, 0
	v_accvgpr_write_b32 a105, 0
	v_accvgpr_write_b32 a104, 0
	v_accvgpr_write_b32 a103, 0
	v_accvgpr_write_b32 a102, 0
	v_accvgpr_write_b32 a101, 0
	v_accvgpr_write_b32 a100, 0
	v_accvgpr_write_b32 a95, 0
	v_accvgpr_write_b32 a94, 0
	v_accvgpr_write_b32 a93, 0
	v_accvgpr_write_b32 a92, 0
	v_accvgpr_write_b32 a91, 0
	v_accvgpr_write_b32 a90, 0
	v_accvgpr_write_b32 a89, 0
	v_accvgpr_write_b32 a88, 0
	v_accvgpr_write_b32 a87, 0
	v_accvgpr_write_b32 a86, 0
	v_accvgpr_write_b32 a85, 0
	v_accvgpr_write_b32 a84, 0
	v_accvgpr_write_b32 a79, 0
	v_accvgpr_write_b32 a78, 0
	v_accvgpr_write_b32 a77, 0
	v_accvgpr_write_b32 a76, 0
	v_accvgpr_write_b32 a75, 0
	v_accvgpr_write_b32 a74, 0
	v_accvgpr_write_b32 a73, 0
	v_accvgpr_write_b32 a72, 0
	v_accvgpr_write_b32 a71, 0
	v_accvgpr_write_b32 a70, 0
	v_accvgpr_write_b32 a69, 0
	v_accvgpr_write_b32 a68, 0
	v_accvgpr_write_b32 a63, 0
	v_accvgpr_write_b32 a62, 0
	v_accvgpr_write_b32 a61, 0
	v_accvgpr_write_b32 a60, 0
	v_accvgpr_write_b32 a59, 0
	v_accvgpr_write_b32 a58, 0
	v_accvgpr_write_b32 a57, 0
	v_accvgpr_write_b32 a56, 0
	v_accvgpr_write_b32 a55, 0
	v_accvgpr_write_b32 a54, 0
	v_accvgpr_write_b32 a53, 0
	v_accvgpr_write_b32 a52, 0
	v_accvgpr_write_b32 a47, 0
	v_accvgpr_write_b32 a46, 0
	v_accvgpr_write_b32 a45, 0
	v_accvgpr_write_b32 a44, 0
	v_accvgpr_write_b32 a43, 0
	v_accvgpr_write_b32 a42, 0
	v_accvgpr_write_b32 a41, 0
	v_accvgpr_write_b32 a40, 0
	v_accvgpr_write_b32 a39, 0
	v_accvgpr_write_b32 a38, 0
	v_accvgpr_write_b32 a37, 0
	v_accvgpr_write_b32 a36, 0
	v_accvgpr_write_b32 a31, 0
	v_accvgpr_write_b32 a30, 0
	v_accvgpr_write_b32 a29, 0
	v_accvgpr_write_b32 a28, 0
	v_accvgpr_write_b32 a27, 0
	v_accvgpr_write_b32 a26, 0
	v_accvgpr_write_b32 a25, 0
	v_accvgpr_write_b32 a24, 0
	v_accvgpr_write_b32 a23, 0
	v_accvgpr_write_b32 a22, 0
	v_accvgpr_write_b32 a21, 0
	v_accvgpr_write_b32 a20, 0
	v_accvgpr_write_b32 a15, 0
	v_accvgpr_write_b32 a14, 0
	v_accvgpr_write_b32 a13, 0
	v_accvgpr_write_b32 a12, 0
	s_mov_b32 s1, 0
	s_mov_b64 s[2:3], 0
	s_mov_b32 s7, 0
	v_readfirstlane_b32 s100, v158
	s_waitcnt vmcnt(12)
	s_barrier
	s_add_u32 s101, s100, 0x18000
	v_lshl_add_u64 v[10:11], v[26:27], 0, s[2:3]
	s_add_u32 m0, s101, 0x0
	v_lshl_add_u64 v[14:15], v[10:11], 0, s[74:75]
	global_load_lds_dwordx4 v[14:15], off
	s_add_u32 m0, s101, 0x1000
	v_lshl_add_u64 v[14:15], v[10:11], 0, s[24:25]
	global_load_lds_dwordx4 v[14:15], off
	s_add_u32 m0, s101, 0x2000
	v_lshl_add_u64 v[14:15], v[10:11], 0, s[76:77]
	global_load_lds_dwordx4 v[14:15], off
	s_add_u32 m0, s101, 0x3000
	v_lshl_add_u64 v[14:15], v[10:11], 0, s[26:27]
	global_load_lds_dwordx4 v[14:15], off
	s_add_u32 m0, s101, 0x4000
	v_lshl_add_u64 v[14:15], v[10:11], 0, s[86:87]
	global_load_lds_dwordx4 v[14:15], off
	s_mov_b64 s[4:5], 0x28100
	s_add_u32 m0, s101, 0x5000
	v_lshl_add_u64 v[14:15], v[10:11], 0, s[4:5]
	global_load_lds_dwordx4 v[14:15], off
	ds_read_b128 v[122:125], v157 offset:0
	ds_read_b128 v[126:129], v157 offset:2048
	ds_read_b128 v[130:133], v157 offset:4096
	ds_read_b128 v[134:137], v157 offset:6144
	ds_read_b128 v[90:93], v156 offset:0
	ds_read_b128 v[94:97], v156 offset:2048
	ds_read_b128 v[98:101], v156 offset:4096
	ds_read_b128 v[102:105], v156 offset:6144
	ds_read_b128 v[106:109], v156 offset:8192
	ds_read_b128 v[110:113], v156 offset:10240
	ds_read_b128 v[114:117], v156 offset:12288
	ds_read_b128 v[118:121], v156 offset:14336
; DI f4 mfma16(h8 a, h8 b, f4 c) { return __builtin_amdgcn_mfma_f32_16x16x32_f16(a, b, c, 0, 0, 0); }
; DI h8 lds128(unsigned a) { h8 r; asm volatile("ds_read_b128 %0, %1" : "=v"(r) : "v"(a)); return r; }
; DI void tie(h8& x) { asm volatile("" : "+v"(x)); }
; #define WAIT_LGKM(n) asm volatile("s_waitcnt lgkmcnt(" #n ")" ::: "memory")
; template <bool PRE = false, class AF, class BF>
; DI void gemm256(AF aptr, BF bptr, int nk, char* smem, f4 (&acc)[8][4]) {
;     ...
; #pragma unroll
;     for (int m = 0; m < 8; m++) a0[m] = lds128(base + offA + m * 2048);
; #pragma unroll
;     for (int n = 0; n < 4; n++) b0[n] = lds128(base + offB + n * 2048);
; #pragma unroll
;     for (int m = 0; m < 8; m++) a1[m] = lds128(base + (offA ^ 64) + m * 2048);
; #pragma unroll
;     for (int n = 0; n < 4; n++) b1[n] = lds128(base + (offB ^ 64) + n * 2048);
;     WAIT_LGKM(12);
; #pragma unroll
;     for (int m = 0; m < 8; m++) tie(a0[m]);
; #pragma unroll
;     for (int n = 0; n < 4; n++) tie(b0[n]);
; #pragma unroll
;     for (int m = 0; m < 8; m++)
; #pragma unroll
;       for (int n = 0; n < 4; n++) acc[m][n] = mfma16(a0[m], b0[n], acc[m][n]);
.Lg_e2_loop:
	s_mul_i32 s22, s7, 0xc000
	v_add_u32_e32 v8, s22, v159
	v_add_u32_e32 v9, s22, v160
	s_add_u32 s101, s7, 2
	s_sub_u32 s21, s101, 3
	s_cmp_lt_u32 s101, 3
	s_cselect_b32 s101, s101, s21
	s_mul_i32 s101, s101, 0xc000
	s_add_u32 s101, s101, s100
	s_cmp_lt_u32 s1, 6
	s_waitcnt lgkmcnt(0)
	s_cbranch_scc0 .Lg_e2_h1n
	v_mfma_f32_16x16x32_f16 a[0:3], v[90:93], v[122:125], a[0:3]
	ds_read_b128 a[200:203], v9 offset:0
	v_mfma_f32_16x16x32_f16 a[4:7], v[90:93], v[126:129], a[4:7]
	v_lshl_add_u64 v[10:11], v[26:27], 0, s[2:3]
	s_add_u32 m0, s101, 0x6000
	v_lshl_add_u64 v[14:15], v[10:11], 0, s[80:81]
	global_load_lds_dwordx4 v[14:15], off
	v_mfma_f32_16x16x32_f16 a[8:11], v[90:93], v[130:133], a[8:11]
	ds_read_b128 a[204:207], v9 offset:2048
	v_mfma_f32_16x16x32_f16 a[16:19], v[90:93], v[134:137], a[16:19]
	v_mfma_f32_16x16x32_f16 a[32:35], v[94:97], v[122:125], a[32:35]
	ds_read_b128 a[208:211], v9 offset:4096
	v_mfma_f32_16x16x32_f16 a[48:51], v[94:97], v[126:129], a[48:51]
	s_mov_b64 s[4:5], 0x38100
	s_add_u32 m0, s101, 0x7000
	v_lshl_add_u64 v[14:15], v[10:11], 0, s[4:5]
	global_load_lds_dwordx4 v[14:15], off
	v_mfma_f32_16x16x32_f16 a[64:67], v[94:97], v[130:133], a[64:67]
	ds_read_b128 a[212:215], v9 offset:6144
	v_mfma_f32_16x16x32_f16 a[80:83], v[94:97], v[134:137], a[80:83]
	v_mfma_f32_16x16x32_f16 a[96:99], v[98:101], v[122:125], a[96:99]
	ds_read_b128 v[138:141], v8 offset:0
	v_mfma_f32_16x16x32_f16 a[112:115], v[98:101], v[126:129], a[112:115]
	v_lshl_add_u64 v[12:13], v[28:29], 0, s[2:3]
	s_add_u32 m0, s101, 0x8000
	v_lshl_add_u64 v[14:15], v[12:13], 0, s[74:75]
	global_load_lds_dwordx4 v[14:15], off
	v_mfma_f32_16x16x32_f16 a[124:127], v[98:101], v[130:133], a[124:127]
	ds_read_b128 v[142:145], v8 offset:2048
	v_mfma_f32_16x16x32_f16 a[120:123], v[98:101], v[134:137], a[120:123]
	v_mfma_f32_16x16x32_f16 a[116:119], v[102:105], v[122:125], a[116:119]
	ds_read_b128 v[0:3], v8 offset:4096
	v_mfma_f32_16x16x32_f16 a[108:111], v[102:105], v[126:129], a[108:111]
	s_add_u32 m0, s101, 0x9000
	v_lshl_add_u64 v[14:15], v[12:13], 0, s[24:25]
	global_load_lds_dwordx4 v[14:15], off
	v_mfma_f32_16x16x32_f16 a[104:107], v[102:105], v[130:133], a[104:107]
	ds_read_b128 v[4:7], v8 offset:6144
	v_mfma_f32_16x16x32_f16 a[100:103], v[102:105], v[134:137], a[100:103]
	v_mfma_f32_16x16x32_f16 a[92:95], v[106:109], v[122:125], a[92:95]
	ds_read_b128 v[152:155], v8 offset:8192
	v_mfma_f32_16x16x32_f16 a[88:91], v[106:109], v[126:129], a[88:91]
	s_add_u32 m0, s101, 0xa000
	v_lshl_add_u64 v[14:15], v[12:13], 0, s[76:77]
	global_load_lds_dwordx4 v[14:15], off
	v_mfma_f32_16x16x32_f16 a[84:87], v[106:109], v[130:133], a[84:87]
	ds_read_b128 v[162:165], v8 offset:10240
	v_mfma_f32_16x16x32_f16 a[76:79], v[106:109], v[134:137], a[76:79]
	v_mfma_f32_16x16x32_f16 a[72:75], v[110:113], v[122:125], a[72:75]
	ds_read_b128 v[166:169], v8 offset:12288
	v_mfma_f32_16x16x32_f16 a[68:71], v[110:113], v[126:129], a[68:71]
	s_add_u32 m0, s101, 0xb000
	v_lshl_add_u64 v[14:15], v[12:13], 0, s[26:27]
	global_load_lds_dwordx4 v[14:15], off
	v_mfma_f32_16x16x32_f16 a[60:63], v[110:113], v[130:133], a[60:63]
	ds_read_b128 v[180:183], v8 offset:14336
	v_mfma_f32_16x16x32_f16 a[56:59], v[110:113], v[134:137], a[56:59]
	v_mfma_f32_16x16x32_f16 a[52:55], v[114:117], v[122:125], a[52:55]
	v_mfma_f32_16x16x32_f16 a[44:47], v[114:117], v[126:129], a[44:47]
	s_add_u32 s21, s7, 1
	v_mfma_f32_16x16x32_f16 a[40:43], v[114:117], v[130:133], a[40:43]
	s_cmp_eq_u32 s21, 3
	v_mfma_f32_16x16x32_f16 a[36:39], v[114:117], v[134:137], a[36:39]
	s_cselect_b32 s21, 0, s21
	v_mfma_f32_16x16x32_f16 a[28:31], v[118:121], v[122:125], a[28:31]
	s_mul_i32 s22, s21, 0xc000
	v_mfma_f32_16x16x32_f16 a[24:27], v[118:121], v[126:129], a[24:27]
	v_add_u32_e32 v22, s22, v156
	v_mfma_f32_16x16x32_f16 a[20:23], v[118:121], v[130:133], a[20:23]
	v_add_u32_e32 v23, s22, v157
	v_mfma_f32_16x16x32_f16 a[12:15], v[118:121], v[134:137], a[12:15]
	s_branch .Lg_e2_mid
.Lg_e2_h1n:
	v_mfma_f32_16x16x32_f16 a[0:3], v[90:93], v[122:125], a[0:3]
	ds_read_b128 a[200:203], v9 offset:0
	v_mfma_f32_16x16x32_f16 a[4:7], v[90:93], v[126:129], a[4:7]
	v_mfma_f32_16x16x32_f16 a[8:11], v[90:93], v[130:133], a[8:11]
	ds_read_b128 a[204:207], v9 offset:2048
	v_mfma_f32_16x16x32_f16 a[16:19], v[90:93], v[134:137], a[16:19]
	v_mfma_f32_16x16x32_f16 a[32:35], v[94:97], v[122:125], a[32:35]
	ds_read_b128 a[208:211], v9 offset:4096
	v_mfma_f32_16x16x32_f16 a[48:51], v[94:97], v[126:129], a[48:51]
	v_mfma_f32_16x16x32_f16 a[64:67], v[94:97], v[130:133], a[64:67]
	ds_read_b128 a[212:215], v9 offset:6144
	v_mfma_f32_16x16x32_f16 a[80:83], v[94:97], v[134:137], a[80:83]
	v_mfma_f32_16x16x32_f16 a[96:99], v[98:101], v[122:125], a[96:99]
	ds_read_b128 v[138:141], v8 offset:0
	v_mfma_f32_16x16x32_f16 a[112:115], v[98:101], v[126:129], a[112:115]
	v_mfma_f32_16x16x32_f16 a[124:127], v[98:101], v[130:133], a[124:127]
	ds_read_b128 v[142:145], v8 offset:2048
	v_mfma_f32_16x16x32_f16 a[120:123], v[98:101], v[134:137], a[120:123]
	v_mfma_f32_16x16x32_f16 a[116:119], v[102:105], v[122:125], a[116:119]
	ds_read_b128 v[0:3], v8 offset:4096
	v_mfma_f32_16x16x32_f16 a[108:111], v[102:105], v[126:129], a[108:111]
	v_mfma_f32_16x16x32_f16 a[104:107], v[102:105], v[130:133], a[104:107]
	ds_read_b128 v[4:7], v8 offset:6144
	v_mfma_f32_16x16x32_f16 a[100:103], v[102:105], v[134:137], a[100:103]
	v_mfma_f32_16x16x32_f16 a[92:95], v[106:109], v[122:125], a[92:95]
	ds_read_b128 v[152:155], v8 offset:8192
	v_mfma_f32_16x16x32_f16 a[88:91], v[106:109], v[126:129], a[88:91]
	v_mfma_f32_16x16x32_f16 a[84:87], v[106:109], v[130:133], a[84:87]
	ds_read_b128 v[162:165], v8 offset:10240
	v_mfma_f32_16x16x32_f16 a[76:79], v[106:109], v[134:137], a[76:79]
	v_mfma_f32_16x16x32_f16 a[72:75], v[110:113], v[122:125], a[72:75]
	ds_read_b128 v[166:169], v8 offset:12288
	v_mfma_f32_16x16x32_f16 a[68:71], v[110:113], v[126:129], a[68:71]
	v_mfma_f32_16x16x32_f16 a[60:63], v[110:113], v[130:133], a[60:63]
	ds_read_b128 v[180:183], v8 offset:14336
	v_mfma_f32_16x16x32_f16 a[56:59], v[110:113], v[134:137], a[56:59]
	v_mfma_f32_16x16x32_f16 a[52:55], v[114:117], v[122:125], a[52:55]
	v_mfma_f32_16x16x32_f16 a[44:47], v[114:117], v[126:129], a[44:47]
	s_add_u32 s21, s7, 1
	v_mfma_f32_16x16x32_f16 a[40:43], v[114:117], v[130:133], a[40:43]
	s_cmp_eq_u32 s21, 3
	v_mfma_f32_16x16x32_f16 a[36:39], v[114:117], v[134:137], a[36:39]
	s_cselect_b32 s21, 0, s21
	v_mfma_f32_16x16x32_f16 a[28:31], v[118:121], v[122:125], a[28:31]
	s_mul_i32 s22, s21, 0xc000
	v_mfma_f32_16x16x32_f16 a[24:27], v[118:121], v[126:129], a[24:27]
	v_add_u32_e32 v22, s22, v156
	v_mfma_f32_16x16x32_f16 a[20:23], v[118:121], v[130:133], a[20:23]
	v_add_u32_e32 v23, s22, v157
	v_mfma_f32_16x16x32_f16 a[12:15], v[118:121], v[134:137], a[12:15]
.Lg_e2_mid:
	s_cmp_eq_u32 s1, 7
	s_cbranch_scc1 .Lg_e2_last
	s_cmp_lt_u32 s1, 6
	s_cbranch_scc1 .Lg_e2_w12
	s_waitcnt vmcnt(0) lgkmcnt(0)
	s_branch .Lg_e2_wd

; DI f4 mfma16(h8 a, h8 b, f4 c) { return __builtin_amdgcn_mfma_f32_16x16x32_f16(a, b, c, 0, 0, 0); }
; DI h8 lds128(unsigned a) { h8 r; asm volatile("ds_read_b128 %0, %1" : "=v"(r) : "v"(a)); return r; }
; DI void tie(h8& x) { asm volatile("" : "+v"(x)); }
; #define WAIT_LGKM(n) asm volatile("s_waitcnt lgkmcnt(" #n ")" ::: "memory")
; template <bool PRE = false, class AF, class BF>
; DI void gemm256(AF aptr, BF bptr, int nk, char* smem, f4 (&acc)[8][4]) {
;     ...
;     if (kt + 2 < nk) issue(kt + 2, st == 0 ? 2 : st - 1);
;     const unsigned base = sbase + st * 49152;
;     st = st == 2 ? 0 : st + 1;
;     h8 a0[8], b0[4], a1[8], b1[4];
; #pragma unroll
;     for (int m = 0; m < 8; m++) a0[m] = lds128(base + offA + m * 2048);
; #pragma unroll
;     for (int n = 0; n < 4; n++) b0[n] = lds128(base + offB + n * 2048);
; #pragma unroll
;     for (int m = 0; m < 8; m++) a1[m] = lds128(base + (offA ^ 64) + m * 2048);
; #pragma unroll
;     for (int n = 0; n < 4; n++) b1[n] = lds128(base + (offB ^ 64) + n * 2048);
;     WAIT_LGKM(12);
; #pragma unroll
;     for (int m = 0; m < 8; m++) tie(a0[m]);
; #pragma unroll
;     for (int n = 0; n < 4; n++) tie(b0[n]);
; #pragma unroll
;     for (int m = 0; m < 8; m++)
; #pragma unroll
;       for (int n = 0; n < 4; n++) acc[m][n] = mfma16(a0[m], b0[n], acc[m][n]);
;     WAIT_LGKM(0);
; #pragma unroll
;     for (int m = 0; m < 8; m++) tie(a1[m]);
; #pragma unroll
;     for (int n = 0; n < 4; n++) tie(b1[n]);
; #pragma unroll
;     for (int m = 0; m < 8; m++)
; #pragma unroll
;       for (int n = 0; n < 4; n++) acc[m][n] = mfma16(a1[m], b1[n], acc[m][n]);
.Lg_e2_wd:
	s_barrier
	s_add_u32 s2, s2, 0x80
	s_addc_u32 s3, s3, 0
	s_mul_i32 s101, s7, 0xc000
	s_add_u32 s101, s101, s100
	s_cmp_lt_u32 s1, 5
	s_cbranch_scc0 .Lg_e2_noissue
	v_mfma_f32_16x16x32_f16 a[0:3], v[138:141], a[200:203], a[0:3]
	ds_read_b128 v[122:125], v23 offset:0
	v_mfma_f32_16x16x32_f16 a[4:7], v[138:141], a[204:207], a[4:7]
	v_lshl_add_u64 v[10:11], v[26:27], 0, s[2:3]
	s_add_u32 m0, s101, 0x0
	v_lshl_add_u64 v[14:15], v[10:11], 0, s[74:75]
	global_load_lds_dwordx4 v[14:15], off
	v_mfma_f32_16x16x32_f16 a[8:11], v[138:141], a[208:211], a[8:11]
	ds_read_b128 v[126:129], v23 offset:2048
	v_mfma_f32_16x16x32_f16 a[16:19], v[138:141], a[212:215], a[16:19]
	v_mfma_f32_16x16x32_f16 a[32:35], v[142:145], a[200:203], a[32:35]
	ds_read_b128 v[130:133], v23 offset:4096
	v_mfma_f32_16x16x32_f16 a[48:51], v[142:145], a[204:207], a[48:51]
	s_add_u32 m0, s101, 0x1000
	v_lshl_add_u64 v[14:15], v[10:11], 0, s[24:25]
	global_load_lds_dwordx4 v[14:15], off
	v_mfma_f32_16x16x32_f16 a[64:67], v[142:145], a[208:211], a[64:67]
	ds_read_b128 v[134:137], v23 offset:6144
	v_mfma_f32_16x16x32_f16 a[80:83], v[142:145], a[212:215], a[80:83]
	v_mfma_f32_16x16x32_f16 a[96:99], v[0:3], a[200:203], a[96:99]
	ds_read_b128 v[90:93], v22 offset:0
	v_mfma_f32_16x16x32_f16 a[112:115], v[0:3], a[204:207], a[112:115]
	s_add_u32 m0, s101, 0x2000
	v_lshl_add_u64 v[14:15], v[10:11], 0, s[76:77]
	global_load_lds_dwordx4 v[14:15], off
	v_mfma_f32_16x16x32_f16 a[124:127], v[0:3], a[208:211], a[124:127]
	ds_read_b128 v[94:97], v22 offset:2048
	v_mfma_f32_16x16x32_f16 a[120:123], v[0:3], a[212:215], a[120:123]
	v_mfma_f32_16x16x32_f16 a[116:119], v[4:7], a[200:203], a[116:119]
	ds_read_b128 v[98:101], v22 offset:4096
	v_mfma_f32_16x16x32_f16 a[108:111], v[4:7], a[204:207], a[108:111]
	s_add_u32 m0, s101, 0x3000
	v_lshl_add_u64 v[14:15], v[10:11], 0, s[26:27]
	global_load_lds_dwordx4 v[14:15], off
	v_mfma_f32_16x16x32_f16 a[104:107], v[4:7], a[208:211], a[104:107]
	ds_read_b128 v[102:105], v22 offset:6144
	v_mfma_f32_16x16x32_f16 a[100:103], v[4:7], a[212:215], a[100:103]
	v_mfma_f32_16x16x32_f16 a[92:95], v[152:155], a[200:203], a[92:95]
	ds_read_b128 v[106:109], v22 offset:8192
	v_mfma_f32_16x16x32_f16 a[88:91], v[152:155], a[204:207], a[88:91]
	s_add_u32 m0, s101, 0x4000
	v_lshl_add_u64 v[14:15], v[10:11], 0, s[86:87]
	global_load_lds_dwordx4 v[14:15], off
	v_mfma_f32_16x16x32_f16 a[84:87], v[152:155], a[208:211], a[84:87]
	ds_read_b128 v[110:113], v22 offset:10240
	v_mfma_f32_16x16x32_f16 a[76:79], v[152:155], a[212:215], a[76:79]
	v_mfma_f32_16x16x32_f16 a[72:75], v[162:165], a[200:203], a[72:75]
	ds_read_b128 v[114:117], v22 offset:12288
	v_mfma_f32_16x16x32_f16 a[68:71], v[162:165], a[204:207], a[68:71]
	s_mov_b64 s[4:5], 0x28100
	s_add_u32 m0, s101, 0x5000
	v_lshl_add_u64 v[14:15], v[10:11], 0, s[4:5]
	global_load_lds_dwordx4 v[14:15], off
	v_mfma_f32_16x16x32_f16 a[60:63], v[162:165], a[208:211], a[60:63]
	ds_read_b128 v[118:121], v22 offset:14336
	v_mfma_f32_16x16x32_f16 a[56:59], v[162:165], a[212:215], a[56:59]
	v_mfma_f32_16x16x32_f16 a[52:55], v[166:169], a[200:203], a[52:55]
	v_mfma_f32_16x16x32_f16 a[44:47], v[166:169], a[204:207], a[44:47]
	v_mfma_f32_16x16x32_f16 a[40:43], v[166:169], a[208:211], a[40:43]
	v_mfma_f32_16x16x32_f16 a[36:39], v[166:169], a[212:215], a[36:39]
	v_mfma_f32_16x16x32_f16 a[28:31], v[180:183], a[200:203], a[28:31]
	v_mfma_f32_16x16x32_f16 a[24:27], v[180:183], a[204:207], a[24:27]
	v_mfma_f32_16x16x32_f16 a[20:23], v[180:183], a[208:211], a[20:23]
	v_mfma_f32_16x16x32_f16 a[12:15], v[180:183], a[212:215], a[12:15]
	s_branch .Lg_e2_next
.Lg_e2_noissue:
	v_mfma_f32_16x16x32_f16 a[0:3], v[138:141], a[200:203], a[0:3]
	ds_read_b128 v[122:125], v23 offset:0
	v_mfma_f32_16x16x32_f16 a[4:7], v[138:141], a[204:207], a[4:7]
	v_mfma_f32_16x16x32_f16 a[8:11], v[138:141], a[208:211], a[8:11]
	ds_read_b128 v[126:129], v23 offset:2048
	v_mfma_f32_16x16x32_f16 a[16:19], v[138:141], a[212:215], a[16:19]
	v_mfma_f32_16x16x32_f16 a[32:35], v[142:145], a[200:203], a[32:35]
	ds_read_b128 v[130:133], v23 offset:4096
	v_mfma_f32_16x16x32_f16 a[48:51], v[142:145], a[204:207], a[48:51]
	v_mfma_f32_16x16x32_f16 a[64:67], v[142:145], a[208:211], a[64:67]
	ds_read_b128 v[134:137], v23 offset:6144
	v_mfma_f32_16x16x32_f16 a[80:83], v[142:145], a[212:215], a[80:83]
	v_mfma_f32_16x16x32_f16 a[96:99], v[0:3], a[200:203], a[96:99]
	ds_read_b128 v[90:93], v22 offset:0
	v_mfma_f32_16x16x32_f16 a[112:115], v[0:3], a[204:207], a[112:115]
	v_mfma_f32_16x16x32_f16 a[124:127], v[0:3], a[208:211], a[124:127]
	ds_read_b128 v[94:97], v22 offset:2048
	v_mfma_f32_16x16x32_f16 a[120:123], v[0:3], a[212:215], a[120:123]
	v_mfma_f32_16x16x32_f16 a[116:119], v[4:7], a[200:203], a[116:119]
	ds_read_b128 v[98:101], v22 offset:4096
	v_mfma_f32_16x16x32_f16 a[108:111], v[4:7], a[204:207], a[108:111]
	v_mfma_f32_16x16x32_f16 a[104:107], v[4:7], a[208:211], a[104:107]
	ds_read_b128 v[102:105], v22 offset:6144
	v_mfma_f32_16x16x32_f16 a[100:103], v[4:7], a[212:215], a[100:103]
	v_mfma_f32_16x16x32_f16 a[92:95], v[152:155], a[200:203], a[92:95]
	ds_read_b128 v[106:109], v22 offset:8192
	v_mfma_f32_16x16x32_f16 a[88:91], v[152:155], a[204:207], a[88:91]
	v_mfma_f32_16x16x32_f16 a[84:87], v[152:155], a[208:211], a[84:87]
	ds_read_b128 v[110:113], v22 offset:10240
	v_mfma_f32_16x16x32_f16 a[76:79], v[152:155], a[212:215], a[76:79]
	v_mfma_f32_16x16x32_f16 a[72:75], v[162:165], a[200:203], a[72:75]
	ds_read_b128 v[114:117], v22 offset:12288
	v_mfma_f32_16x16x32_f16 a[68:71], v[162:165], a[204:207], a[68:71]
	v_mfma_f32_16x16x32_f16 a[60:63], v[162:165], a[208:211], a[60:63]
	ds_read_b128 v[118:121], v22 offset:14336
	v_mfma_f32_16x16x32_f16 a[56:59], v[162:165], a[212:215], a[56:59]
	v_mfma_f32_16x16x32_f16 a[52:55], v[166:169], a[200:203], a[52:55]
	v_mfma_f32_16x16x32_f16 a[44:47], v[166:169], a[204:207], a[44:47]
	v_mfma_f32_16x16x32_f16 a[40:43], v[166:169], a[208:211], a[40:43]
	v_mfma_f32_16x16x32_f16 a[36:39], v[166:169], a[212:215], a[36:39]
	v_mfma_f32_16x16x32_f16 a[28:31], v[180:183], a[200:203], a[28:31]
	v_mfma_f32_16x16x32_f16 a[24:27], v[180:183], a[204:207], a[24:27]
	v_mfma_f32_16x16x32_f16 a[20:23], v[180:183], a[208:211], a[20:23]
	v_mfma_f32_16x16x32_f16 a[12:15], v[180:183], a[212:215], a[12:15]
.Lg_e2_next:
	s_mov_b32 s7, s21
	s_add_u32 s1, s1, 1
	s_branch .Lg_e2_loop
